# add E3 L0 swapped-MFMA coalesced epilogue (f32 residual source) on top of v26
# speedup vs baseline: 1.0123x; 1.0025x over previous
; template <class Epi, class Sched>
; __device__ __forceinline__ void gemm_phase(LAS unsigned char* lds, const int K, const int lda, const int ldb, const Sched& S, const Epi& E) {
;     ...
;     for (int i = 0; i < 2; ++i) { int R, C; stage_rc(tid * 16 + i * 8192, R, C); const int Rb = (R & ~31) + perm32(R & 31);
;         voffA[i] = (unsigned)(R * lda + C) * 2u; voffB[i] = (unsigned)(Rb * ldb + C) * 2u; }
;     const size_t kstep = (size_t)(BK * 2);
;     const size_t hA = (size_t)HALF * lda * 2, hB = (size_t)HALF * ldb * 2;
;     const unsigned ldsw = (unsigned)wid * 1024u;
;     const int aoff = lds_byte(wr * 64 + fr, fq * 8), boff = lds_byte(wc * 32 + fr, fq * 8);
.LBB0_606:
	v_readlane_b32 s0, v255, 24
	v_readlane_b32 s1, v255, 25
	s_and_b64 vcc, exec, s[0:1]
	s_cbranch_vccnz .LBB0_644
	v_ashrrev_i32_e32 v1, 31, v8
	v_lshrrev_b32_e32 v1, 26, v1
	v_add_u32_e32 v1, v8, v1
	v_ashrrev_i32_e32 v9, 6, v1
	v_bfe_i32 v1, v8, 27, 1
	v_lshlrev_b32_e32 v0, 4, v8
	v_lshrrev_b32_e32 v1, 22, v1
	v_add_u32_e32 v1, v0, v1
	v_and_b32_e32 v1, 0xfffffc00, v1
	v_sub_u32_e32 v1, v0, v1
	v_lshrrev_b32_e32 v2, 4, v1
	v_bitop3_b32 v1, v2, v1, 32 bitop3:0x6c
	v_ashrrev_i32_e32 v3, 31, v1
	v_lshrrev_b32_e32 v3, 26, v3
	v_add_u32_e32 v3, v1, v3
	v_lshlrev_b32_e32 v2, 3, v9
	v_ashrrev_i32_e32 v10, 6, v3
	v_and_b32_e32 v3, 0xc0, v3
	v_and_b32_e32 v2, -16, v2
	v_sub_u32_e32 v1, v1, v3
	v_mov_b32_e32 v3, 1
	v_add_u32_e32 v2, v10, v2
	v_ashrrev_i16_sdwa v1, v3, sext(v1) dst_sel:DWORD dst_unused:UNUSED_PAD src0_sel:DWORD src1_sel:BYTE_0
	v_lshlrev_b32_e32 v4, 5, v9
	v_bfe_i32 v11, v1, 0, 16
	v_lshlrev_b32_e32 v1, 1, v2
	v_lshrrev_b32_e32 v5, 2, v2
	v_and_b32_e32 v6, 3, v10
	s_mov_b32 s1, 0xfffe0
	v_and_b32_e32 v4, 32, v4
	v_and_b32_e32 v1, 24, v1
	v_and_b32_e32 v5, 4, v5
	v_and_or_b32 v6, v2, s1, v6
	v_or3_b32 v1, v6, v5, v1
	v_add_lshl_u32 v4, v4, v11, 1
	v_add_u32_e32 v0, 0x2000, v0
	v_and_b32_e32 v106, 63, v254
	v_lshrrev_b32_e32 v107, 6, v254
	v_lshrrev_b32_e32 v108, 3, v106
	v_lshl_add_u32 v109, v107, 3, v108
	v_and_b32_e32 v110, 1, v107
	v_bfe_u32 v111, v106, 4, 2
	v_lshl_add_u32 v111, v110, 2, v111
	v_and_b32_e32 v101, 7, v106
	v_xor_b32_e32 v111, v101, v111
	v_lshlrev_b32_e32 v111, 4, v111
	v_lshl_add_u32 v100, v109, 12, v111
	v_add_u32_e32 v101, 0x40000, v100
	v_lshrrev_b32_e32 v109, 5, v106
	v_lshlrev_b32_e32 v109, 3, v109
	v_lshl_add_u32 v109, v110, 4, v109
	v_bfe_u32 v110, v107, 1, 1
	v_lshl_add_u32 v109, v110, 2, v109
	v_and_b32_e32 v110, 3, v108
	v_add_u32_e32 v109, v109, v110
	v_lshrrev_b32_e32 v110, 2, v107
	v_lshl_add_u32 v109, v110, 5, v109
	v_lshl_add_u32 v102, v109, 12, v111
	v_add_u32_e32 v103, 0x40000, v102
	v_and_b32_e32 v106, 15, v254
	v_bfe_u32 v108, v254, 4, 2
	v_bfe_u32 v109, v254, 1, 3
	v_xor_b32_e32 v108, v108, v109
	v_lshlrev_b32_e32 v108, 4, v108
	v_lshl_add_u32 v108, v106, 7, v108
	v_lshrrev_b32_e32 v109, 8, v254
	v_lshl_add_u32 v104, v109, 13, v108
	v_and_b32_e32 v109, 3, v107
	v_lshl_add_u32 v105, v109, 13, v108
	v_and_b32_e32 v106, 63, v254
	v_lshrrev_b32_e32 v107, 6, v254
	v_lshrrev_b32_e32 v108, 3, v106
	v_and_b32_e32 v110, 1, v107
	v_bfe_u32 v111, v106, 4, 2
	v_lshl_add_u32 v111, v110, 2, v111
	v_and_b32_e32 v109, 7, v106
	v_xor_b32_e32 v111, v109, v111
	v_lshlrev_b32_e32 v111, 4, v111
	v_lshlrev_b32_e32 v109, 5, v110
	v_lshl_add_u32 v109, v108, 2, v109
	v_bfe_u32 v110, v107, 1, 2
	v_add_u32_e32 v109, v109, v110
	v_lshl_add_u32 v102, v109, 12, v111
	v_add_u32_e32 v103, 0x40000, v102
	v_mov_b32_e32 v178, v102
	v_ashrrev_i32_e32 v1, 31, v0
	v_lshrrev_b32_e32 v1, 22, v1
	v_add_u32_e32 v1, v0, v1
	v_ashrrev_i32_e32 v12, 10, v1
	v_mul_i32_i24_e32 v1, 0x400, v12
	v_sub_u32_e32 v0, v0, v1
	v_lshrrev_b32_e32 v1, 4, v0
	v_bitop3_b32 v0, v1, v0, 32 bitop3:0x6c
	v_mov_b32_e32 v176, v100
	v_ashrrev_i32_e32 v2, 31, v0
	v_lshrrev_b32_e32 v2, 26, v2
	v_add_u32_e32 v2, v0, v2
	v_lshlrev_b32_e32 v1, 3, v12
	v_ashrrev_i32_e32 v13, 6, v2
	v_and_b32_e32 v2, 0xc0, v2
	v_and_b32_e32 v1, -16, v1
	v_sub_u32_e32 v0, v0, v2
	s_ashr_i32 s0, s8, 6
	v_add_u32_e32 v1, v13, v1
	v_ashrrev_i16_sdwa v0, v3, sext(v0) dst_sel:DWORD dst_unused:UNUSED_PAD src0_sel:DWORD src1_sel:BYTE_0
	v_and_b32_e32 v3, 3, v13
	v_and_or_b32 v3, v1, s1, v3
	s_ashr_i32 s6, s8, 8
	s_lshl_b32 s1, s0, 10
	s_add_u32 s2, s36, 0x2600000
	s_addc_u32 s4, s37, 0
	s_ashr_i32 s61, s60, 31
	s_ashr_i32 s47, s46, 31
	s_lshl_b64 s[14:15], s[60:61], 20
	s_lshl_b64 s[18:19], s[46:47], 20
	s_add_u32 s62, s2, s18
	v_lshlrev_b32_e32 v4, 5, v12
	v_bfe_i32 v14, v0, 0, 16
	v_lshlrev_b32_e32 v0, 1, v1
	v_lshrrev_b32_e32 v2, 2, v1
	s_addc_u32 s63, s4, s19
	s_add_i32 s5, s1, 0
	v_and_b32_e32 v4, 32, v4
	v_and_b32_e32 v0, 24, v0
	v_and_b32_e32 v2, 4, v2
	s_add_i32 m0, s5, 0x10000
	v_or3_b32 v0, v3, v2, v0
	v_add_lshl_u32 v2, v4, v14, 1
	global_load_lds_dwordx4 v178, s[62:63]
	s_add_i32 m0, s5, 0x12000
	v_mov_b32_e32 v182, v103
	s_add_u32 s18, s62, 0x80000
	global_load_lds_dwordx4 v182, s[62:63]
	s_addc_u32 s19, s63, 0
	s_add_i32 m0, s5, 0x14000
	v_mov_b32_e32 v180, v101
	global_load_lds_dwordx4 v178, s[18:19]
	s_add_i32 m0, s5, 0x16000
	s_add_u32 s64, s42, s14
	s_addc_u32 s65, s43, s15
	s_add_i32 s14, s5, 0x2000
	global_load_lds_dwordx4 v182, s[18:19]
	s_mov_b32 m0, s5
	s_add_u32 s18, s64, 0x80000
	global_load_lds_dwordx4 v176, s[64:65]
	s_mov_b32 m0, s14
	s_addc_u32 s19, s65, 0
	s_add_i32 s15, s5, 0x4000
	global_load_lds_dwordx4 v180, s[64:65]
	s_mov_b32 m0, s15
	s_add_i32 s17, s5, 0x6000
	global_load_lds_dwordx4 v176, s[18:19]
	s_mov_b32 m0, s17
	v_mov_b32_e32 v179, 0
	global_load_lds_dwordx4 v180, s[18:19]
	v_mov_b32_e32 v183, v179
	v_mov_b32_e32 v177, v179
	v_mov_b32_e32 v181, v179
	s_cmp_eq_u32 s6, 1
	s_mov_b32 s21, 0
	v_lshl_add_u64 v[6:7], s[62:63], 0, v[178:179]
	v_lshl_add_u64 v[4:5], s[62:63], 0, v[182:183]
	v_lshl_add_u64 v[0:1], s[64:65], 0, v[176:177]
	s_cselect_b64 s[36:37], -1, 0
	s_cmp_lg_u32 s6, 1
	v_lshl_add_u64 v[2:3], s[64:65], 0, v[180:181]
	s_cbranch_scc1 .LBB0_609
	s_barrier
; #define PG8_STAGE(bufoff, gbase, voff) do { _Pragma("unroll") for (int _i = 0; _i < 2; ++_i) \
;         __builtin_amdgcn_global_load_lds((const unsigned*)((const char*)(gbase) + (voff)[_i]), (LAS unsigned*)(lds + (bufoff) + ldsw + _i * 8192), 16, 0, 0); } while (0)
; #define PG8_WAIT_V(n) asm volatile("s_waitcnt vmcnt(" #n ")" ::: "memory")
; #define PG8_BAR __builtin_amdgcn_s_barrier()
; template <class Epi, class Sched>
; __device__ __forceinline__ void gemm_phase(LAS unsigned char* lds, const int K, const int lda, const int ldb, const Sched& S, const Epi& E) {
;     ...
;     PG8_STAGE(PG8_SB(0, 0), cB, voffB); PG8_STAGE(PG8_SB(0, 1), cB + hB, voffB); PG8_STAGE(PG8_SA(0, 0), cA, voffA); PG8_STAGE(PG8_SA(0, 1), cA + hA, voffA);
;     if (wr == 1) PG8_BAR;
;     PG8_WAIT_V(2); PG8_BAR;
;     PG8_STAGE(PG8_SB(1, 0), cB + kstep, voffB); PG8_STAGE(PG8_SA(1, 0), cA + kstep, voffA); PG8_STAGE(PG8_SB(1, 1), cB + hB + kstep, voffB);
;     PG8_WAIT_V(6); PG8_BAR;
.LBB0_609:
	s_mov_b64 s[48:49], 0x80
	s_and_b32 s9, s0, 3
	s_add_i32 m0, s5, 0x18000
	v_lshl_add_u64 v[6:7], v[6:7], 0, s[48:49]
	s_lshl_b32 s23, s6, 6
	s_lshl_b32 s18, s6, 13
	s_lshl_b32 s19, s9, 12
	s_waitcnt vmcnt(2)
	s_barrier
	global_load_lds_dwordx4 v[6:7], off
	v_lshl_add_u64 v[4:5], v[4:5], 0, s[48:49]
	s_add_i32 m0, s5, 0x1a000
	s_add_i32 s0, s5, 0x8000
	s_add_i32 s24, s5, 0xa000
	global_load_lds_dwordx4 v[4:5], off
	v_lshl_add_u64 v[0:1], v[0:1], 0, s[48:49]
	s_mov_b32 m0, s0
	s_add_u32 s6, s62, 0x80080
	global_load_lds_dwordx4 v[0:1], off
	v_lshl_add_u64 v[0:1], v[2:3], 0, s[48:49]
	s_mov_b32 m0, s24
	s_addc_u32 s7, s63, 0
	global_load_lds_dwordx4 v[0:1], off
	s_add_i32 m0, s5, 0x1c000
	v_lshl_add_u64 v[0:1], s[6:7], 0, v[178:179]
	global_load_lds_dwordx4 v[0:1], off
	v_lshl_add_u64 v[0:1], s[6:7], 0, v[182:183]
	s_add_i32 m0, s5, 0x1e000
	v_lshrrev_b32_e32 v2, 1, v8
	global_load_lds_dwordx4 v[0:1], off
	v_and_b32_e32 v2, 24, v2
	v_and_b32_e32 v204, 15, v8
	v_and_b32_e32 v3, 48, v8
	v_lshlrev_b32_e32 v4, 2, v8
	v_lshl_or_b32 v206, s9, 5, v2
	v_lshlrev_b32_e32 v2, 15, v12
	v_lshl_or_b32 v3, v204, 6, v3
	v_and_b32_e32 v4, 32, v4
	v_and_b32_e32 v2, 0xffff0000, v2
	v_bitop3_b32 v5, v3, s18, v4 bitop3:0xde
	v_mov_b32_e32 v205, v105
	s_cmpk_lt_u32 s8, 0x100
	v_lshl_add_u32 v2, v13, 12, v2
	v_and_b32_e32 v3, 1, v12
	s_cselect_b64 s[50:51], -1, 0
	s_lshl_b32 s6, s9, 2
	v_lshl_or_b32 v2, v3, 6, v2
	v_and_b32_e32 v0, 63, v8
	v_or_b32_e32 v1, s23, v204
	s_add_i32 s6, s6, 0
	v_mov_b32_e32 v184, v101
	v_lshlrev_b32_e32 v2, 15, v9
	s_add_i32 s19, s6, 0x20000
	v_cmp_gt_u32_e64 s[6:7], 16, v0
	v_lshlrev_b32_e32 v0, 4, v1
	s_movk_i32 s9, 0xffc0
	v_mov_b32_e32 v1, s8
	v_and_b32_e32 v2, 0xffff0000, v2
	v_bfi_b32 v207, s9, v1, v8
	s_ashr_i32 s25, s3, 31
	s_ashr_i32 s26, s33, 31
	v_lshl_add_u32 v2, v10, 12, v2
	v_and_b32_e32 v3, 1, v9
	s_waitcnt vmcnt(6)
	v_lshlrev_b32_e32 v1, 4, v207
	s_waitcnt lgkmcnt(0)
	s_add_u32 s27, s10, 0xf8000000
	v_lshl_or_b32 v2, v3, 6, v2
	s_movk_i32 s18, 0x100
	s_addc_u32 s28, s11, -1
	v_mov_b32_e32 v186, v100
	s_add_i32 s29, 0, 0x10000
	s_add_i32 s34, 0, 0x14000
	v_mbcnt_lo_u32_b32 v2, -1, 0
	v_add_u32_e32 v1, 0, v1
	v_cmp_gt_i32_e64 s[8:9], s18, v207
	v_mov_b32_e32 v185, v179
	v_mov_b32_e32 v187, v179
	v_mov_b64_e32 v[188:189], 0x400
	v_mov_b64_e32 v[190:191], 0x3ff
	v_add_u32_e32 v208, s29, v205
	v_add_u32_e32 v209, 0x11000, v205
	v_mov_b32_e32 v210, v104
	v_xor_b32_e32 v234, 64, v210
	v_xor_b32_e32 v235, 64, v208
	v_xor_b32_e32 v236, 64, v209
	v_xor_b32_e32 v237, 64, v205
	v_mbcnt_hi_u32_b32 v211, -1, v2
	v_add_u32_e32 v212, 0x20000, v1
	v_add_u32_e32 v213, s19, v0
	s_barrier
	s_branch .LBB0_612

; #define PG8_STAGE(bufoff, gbase, voff) do { _Pragma("unroll") for (int _i = 0; _i < 2; ++_i) \
;         __builtin_amdgcn_global_load_lds((const unsigned*)((const char*)(gbase) + (voff)[_i]), (LAS unsigned*)(lds + (bufoff) + ldsw + _i * 8192), 16, 0, 0); } while (0)
; #define PG8_LDA(dst, b, h) do { _Pragma("unroll") for (int m = 0; m < 4; ++m) _Pragma("unroll") for (int k = 0; k < 2; ++k) dst[m][k] = *(const LAS bf16x8*)(lds + PG8_SA(b, h) + aoff + m * 2048 + k * 1024); } while (0)
; #define PG8_LDB(dst, b, h) do { _Pragma("unroll") for (int n = 0; n < 2; ++n) _Pragma("unroll") for (int k = 0; k < 2; ++k) dst[n][k] = *(const LAS bf16x8*)(lds + PG8_SB(b, h) + boff + n * 2048 + k * 1024); } while (0)
; #define PG8_MMA(ai, bj, At, Bt) do { __builtin_amdgcn_s_setprio(1); _Pragma("unroll") for (int m = 0; m < 4; ++m) _Pragma("unroll") for (int n = 0; n < 2; ++n) _Pragma("unroll") for (int k = 0; k < 2; ++k) \
;         acc[ai][bj][m][n] = __builtin_amdgcn_mfma_f32_16x16x32_bf16(Bt[n][k], At[m][k], acc[ai][bj][m][n], 0, 0, 0); __builtin_amdgcn_s_setprio(0); } while (0)
; #define PG8_WAIT_V(n) asm volatile("s_waitcnt vmcnt(" #n ")" ::: "memory")
; #define PG8_WAIT_L(n) asm volatile("s_waitcnt lgkmcnt(" #n ")" ::: "memory")
; #define PG8_BAR __builtin_amdgcn_s_barrier()
; #define PG8_SCHED __builtin_amdgcn_sched_barrier(0)
; template <class Epi, class Sched>
; __device__ __forceinline__ void gemm_phase(LAS unsigned char* lds, const int K, const int lda, const int ldb, const Sched& S, const Epi& E) {
;     ...
;             PG8_LDB(B0, 0, 0); PG8_LDB(B1, 0, 1); PG8_SCHED; PG8_LDA(At, 0, 0); PG8_STAGE(PG8_SA(1, 1), a1 + hA, voffA);
;             PG8_WAIT_V(8); PG8_WAIT_L(0); PG8_BAR; PG8_MMA(0, 0, At, B0); PG8_MMA(0, 1, At, B1); PG8_BAR; PG8_SCHED;
;             PG8_LDA(At, 0, 1); PG8_STAGE(PG8_SB(0, 0), b2, voffB); PG8_STAGE(PG8_SB(0, 1), b2 + hB, voffB); PG8_STAGE(PG8_SA(0, 0), a2, voffA);
;             PG8_WAIT_V(8); PG8_WAIT_L(0); PG8_BAR; PG8_MMA(1, 0, At, B0); PG8_MMA(1, 1, At, B1); PG8_BAR; PG8_SCHED;
.LBB0_619:
	ds_read_b128 v[128:131], v208
	ds_read_b128 v[132:135], v235
	ds_read_b128 v[136:139], v208 offset:2048
	ds_read_b128 v[140:143], v235 offset:2048
	ds_read_b128 v[144:147], v209
	ds_read_b128 v[148:151], v236
	ds_read_b128 v[152:155], v209 offset:2048
	ds_read_b128 v[156:159], v236 offset:2048
	s_add_u32 s53, s62, 0xfff80080
	s_addc_u32 s55, s63, -1
	s_cmp_eq_u32 s47, 28
	s_cselect_b32 s67, s18, s55
	s_cselect_b32 s66, s19, s53
	s_cselect_b32 s65, s35, s41
	s_cselect_b32 s64, s38, s39
	v_lshl_add_u64 v[218:219], s[62:63], 0, v[186:187]
	s_add_i32 m0, s5, 0xc000
	ds_read_b128 v[160:163], v210
	ds_read_b128 v[164:167], v234
	ds_read_b128 v[168:171], v210 offset:2048
	ds_read_b128 v[172:175], v234 offset:2048
	ds_read_b128 v[192:195], v210 offset:4096
	ds_read_b128 v[196:199], v234 offset:4096
	ds_read_b128 v[200:203], v210 offset:6144
	ds_read_b128 v[214:217], v234 offset:6144
	global_load_lds_dwordx4 v[218:219], off
	v_lshl_add_u64 v[218:219], s[62:63], 0, v[184:185]
	s_add_i32 m0, s5, 0xe000
	s_nop 0
	global_load_lds_dwordx4 v[218:219], off
	s_waitcnt vmcnt(8)
	s_waitcnt lgkmcnt(0)
	s_barrier
	s_setprio 1
	s_waitcnt lgkmcnt(0)
	v_mfma_f32_16x16x32_bf16 v[124:127], v[160:163], v[128:131], v[124:127]
	v_mfma_f32_16x16x32_bf16 v[120:123], v[160:163], v[136:139], v[120:123]
	v_mfma_f32_16x16x32_bf16 v[108:111], v[168:171], v[128:131], v[108:111]
	v_mfma_f32_16x16x32_bf16 v[104:107], v[168:171], v[136:139], v[104:107]
	v_mfma_f32_16x16x32_bf16 v[92:95], v[192:195], v[128:131], v[92:95]
	v_mfma_f32_16x16x32_bf16 v[88:91], v[192:195], v[136:139], v[88:91]
	v_mfma_f32_16x16x32_bf16 v[76:79], v[200:203], v[128:131], v[76:79]
	v_mfma_f32_16x16x32_bf16 v[72:75], v[200:203], v[136:139], v[72:75]
	v_mfma_f32_16x16x32_bf16 v[124:127], v[164:167], v[132:135], v[124:127]
	v_mfma_f32_16x16x32_bf16 v[120:123], v[164:167], v[140:143], v[120:123]
	v_mfma_f32_16x16x32_bf16 v[108:111], v[172:175], v[132:135], v[108:111]
	v_mfma_f32_16x16x32_bf16 v[104:107], v[172:175], v[140:143], v[104:107]
	v_mfma_f32_16x16x32_bf16 v[92:95], v[196:199], v[132:135], v[92:95]
	v_mfma_f32_16x16x32_bf16 v[88:91], v[196:199], v[140:143], v[88:91]
	v_mfma_f32_16x16x32_bf16 v[76:79], v[214:217], v[132:135], v[76:79]
	v_mfma_f32_16x16x32_bf16 v[72:75], v[214:217], v[140:143], v[72:75]
	s_setprio 0
	s_setprio 1
	v_mfma_f32_16x16x32_bf16 v[116:119], v[160:163], v[144:147], v[116:119]
	v_mfma_f32_16x16x32_bf16 v[112:115], v[160:163], v[152:155], v[112:115]
	v_mfma_f32_16x16x32_bf16 v[100:103], v[168:171], v[144:147], v[100:103]
	v_mfma_f32_16x16x32_bf16 v[96:99], v[168:171], v[152:155], v[96:99]
	v_mfma_f32_16x16x32_bf16 v[84:87], v[192:195], v[144:147], v[84:87]
	v_mfma_f32_16x16x32_bf16 v[80:83], v[192:195], v[152:155], v[80:83]
	v_mfma_f32_16x16x32_bf16 v[68:71], v[200:203], v[144:147], v[68:71]
	v_mfma_f32_16x16x32_bf16 v[64:67], v[200:203], v[152:155], v[64:67]
	v_mfma_f32_16x16x32_bf16 v[116:119], v[164:167], v[148:151], v[116:119]
	v_mfma_f32_16x16x32_bf16 v[112:115], v[164:167], v[156:159], v[112:115]
	v_mfma_f32_16x16x32_bf16 v[100:103], v[172:175], v[148:151], v[100:103]
	v_mfma_f32_16x16x32_bf16 v[96:99], v[172:175], v[156:159], v[96:99]
	v_mfma_f32_16x16x32_bf16 v[84:87], v[196:199], v[148:151], v[84:87]
	v_mfma_f32_16x16x32_bf16 v[80:83], v[196:199], v[156:159], v[80:83]
	v_mfma_f32_16x16x32_bf16 v[68:71], v[214:217], v[148:151], v[68:71]
	v_mfma_f32_16x16x32_bf16 v[64:67], v[214:217], v[156:159], v[64:67]
	s_setprio 0
	s_barrier
	s_add_i32 s53, s29, s1
	v_lshl_add_u64 v[218:219], s[64:65], 0, v[178:179]
	s_mov_b32 m0, s53
	ds_read_b128 v[160:163], v210 offset:16384
	ds_read_b128 v[164:167], v234 offset:16384
	ds_read_b128 v[168:171], v210 offset:18432
	ds_read_b128 v[172:175], v234 offset:18432
	ds_read_b128 v[192:195], v210 offset:20480
	ds_read_b128 v[196:199], v234 offset:20480
	ds_read_b128 v[200:203], v210 offset:22528
	ds_read_b128 v[214:217], v234 offset:22528
	global_load_lds_dwordx4 v[218:219], off
	s_add_i32 m0, s53, 0x2000
	s_add_u32 s68, s64, 0x80000
	v_lshl_add_u64 v[220:221], s[64:65], 0, v[182:183]
	s_addc_u32 s69, s65, 0
	s_add_i32 s53, s34, s1
	global_load_lds_dwordx4 v[220:221], off
	v_lshl_add_u64 v[222:223], s[68:69], 0, v[178:179]
	s_mov_b32 m0, s53
	v_lshl_add_u64 v[224:225], s[66:67], 0, v[180:181]
	global_load_lds_dwordx4 v[222:223], off
	v_lshl_add_u64 v[222:223], s[68:69], 0, v[182:183]
	s_add_i32 m0, s53, 0x2000
	s_nop 0
	global_load_lds_dwordx4 v[222:223], off
	v_lshl_add_u64 v[222:223], s[66:67], 0, v[176:177]
	s_mov_b32 m0, s5
	s_nop 0
	global_load_lds_dwordx4 v[222:223], off
	s_mov_b32 m0, s14
	s_nop 0
	global_load_lds_dwordx4 v[224:225], off
	s_waitcnt vmcnt(8)
	s_waitcnt lgkmcnt(0)
	s_barrier
; #define PG8_STAGE(bufoff, gbase, voff) do { _Pragma("unroll") for (int _i = 0; _i < 2; ++_i) \
;         __builtin_amdgcn_global_load_lds((const unsigned*)((const char*)(gbase) + (voff)[_i]), (LAS unsigned*)(lds + (bufoff) + ldsw + _i * 8192), 16, 0, 0); } while (0)
; #define PG8_LDA(dst, b, h) do { _Pragma("unroll") for (int m = 0; m < 4; ++m) _Pragma("unroll") for (int k = 0; k < 2; ++k) dst[m][k] = *(const LAS bf16x8*)(lds + PG8_SA(b, h) + aoff + m * 2048 + k * 1024); } while (0)
; #define PG8_LDB(dst, b, h) do { _Pragma("unroll") for (int n = 0; n < 2; ++n) _Pragma("unroll") for (int k = 0; k < 2; ++k) dst[n][k] = *(const LAS bf16x8*)(lds + PG8_SB(b, h) + boff + n * 2048 + k * 1024); } while (0)
; #define PG8_MMA(ai, bj, At, Bt) do { __builtin_amdgcn_s_setprio(1); _Pragma("unroll") for (int m = 0; m < 4; ++m) _Pragma("unroll") for (int n = 0; n < 2; ++n) _Pragma("unroll") for (int k = 0; k < 2; ++k) \
;         acc[ai][bj][m][n] = __builtin_amdgcn_mfma_f32_16x16x32_bf16(Bt[n][k], At[m][k], acc[ai][bj][m][n], 0, 0, 0); __builtin_amdgcn_s_setprio(0); } while (0)
; #define PG8_WAIT_V(n) asm volatile("s_waitcnt vmcnt(" #n ")" ::: "memory")
; #define PG8_WAIT_L(n) asm volatile("s_waitcnt lgkmcnt(" #n ")" ::: "memory")
; #define PG8_BAR __builtin_amdgcn_s_barrier()
; #define PG8_SCHED __builtin_amdgcn_sched_barrier(0)
; template <class Epi, class Sched>
; __device__ __forceinline__ void gemm_phase(LAS unsigned char* lds, const int K, const int lda, const int ldb, const Sched& S, const Epi& E) {
;     ...
;             PG8_WAIT_V(8); PG8_WAIT_L(0); PG8_BAR; PG8_MMA(1, 0, At, B0); PG8_MMA(1, 1, At, B1); PG8_BAR; PG8_SCHED;
;             PG8_LDB(B0, 1, 0); PG8_LDB(B1, 1, 1); PG8_SCHED; PG8_LDA(At, 1, 0); PG8_STAGE(PG8_SA(0, 1), a2 + hA, voffA);
;             PG8_WAIT_V(8); PG8_WAIT_L(0); PG8_BAR; PG8_MMA(0, 0, At, B0); PG8_MMA(0, 1, At, B1); PG8_BAR; PG8_SCHED;
;             PG8_LDA(At, 1, 1); PG8_STAGE(PG8_SB(1, 0), b3, voffB); PG8_STAGE(PG8_SB(1, 1), b3 + hB, voffB); PG8_STAGE(PG8_SA(1, 0), a3, voffA);
;             PG8_WAIT_V(8); PG8_WAIT_L(0); PG8_BAR; PG8_MMA(1, 0, At, B0); PG8_MMA(1, 1, At, B1); PG8_BAR; PG8_SCHED;
	s_setprio 1
	s_waitcnt lgkmcnt(0)
	v_mfma_f32_16x16x32_bf16 v[60:63], v[160:163], v[128:131], v[60:63]
	v_mfma_f32_16x16x32_bf16 v[56:59], v[160:163], v[136:139], v[56:59]
	v_mfma_f32_16x16x32_bf16 v[44:47], v[168:171], v[128:131], v[44:47]
	v_mfma_f32_16x16x32_bf16 v[40:43], v[168:171], v[136:139], v[40:43]
	v_mfma_f32_16x16x32_bf16 v[28:31], v[192:195], v[128:131], v[28:31]
	v_mfma_f32_16x16x32_bf16 v[24:27], v[192:195], v[136:139], v[24:27]
	v_mfma_f32_16x16x32_bf16 v[12:15], v[200:203], v[128:131], v[12:15]
	v_mfma_f32_16x16x32_bf16 v[8:11], v[200:203], v[136:139], v[8:11]
	v_mfma_f32_16x16x32_bf16 v[60:63], v[164:167], v[132:135], v[60:63]
	v_mfma_f32_16x16x32_bf16 v[56:59], v[164:167], v[140:143], v[56:59]
	v_mfma_f32_16x16x32_bf16 v[44:47], v[172:175], v[132:135], v[44:47]
	v_mfma_f32_16x16x32_bf16 v[40:43], v[172:175], v[140:143], v[40:43]
	v_mfma_f32_16x16x32_bf16 v[28:31], v[196:199], v[132:135], v[28:31]
	v_mfma_f32_16x16x32_bf16 v[24:27], v[196:199], v[140:143], v[24:27]
	v_mfma_f32_16x16x32_bf16 v[12:15], v[214:217], v[132:135], v[12:15]
	v_mfma_f32_16x16x32_bf16 v[8:11], v[214:217], v[140:143], v[8:11]
	s_setprio 0
	s_setprio 1
	v_mfma_f32_16x16x32_bf16 v[52:55], v[160:163], v[144:147], v[52:55]
	v_mfma_f32_16x16x32_bf16 v[48:51], v[160:163], v[152:155], v[48:51]
	v_mfma_f32_16x16x32_bf16 v[36:39], v[168:171], v[144:147], v[36:39]
	v_mfma_f32_16x16x32_bf16 v[32:35], v[168:171], v[152:155], v[32:35]
	v_mfma_f32_16x16x32_bf16 v[20:23], v[192:195], v[144:147], v[20:23]
	v_mfma_f32_16x16x32_bf16 v[16:19], v[192:195], v[152:155], v[16:19]
	v_mfma_f32_16x16x32_bf16 v[4:7], v[200:203], v[144:147], v[4:7]
	v_mfma_f32_16x16x32_bf16 v[0:3], v[200:203], v[152:155], v[0:3]
	v_mfma_f32_16x16x32_bf16 v[52:55], v[164:167], v[148:151], v[52:55]
	v_mfma_f32_16x16x32_bf16 v[48:51], v[164:167], v[156:159], v[48:51]
	v_mfma_f32_16x16x32_bf16 v[36:39], v[172:175], v[148:151], v[36:39]
	v_mfma_f32_16x16x32_bf16 v[32:35], v[172:175], v[156:159], v[32:35]
	v_mfma_f32_16x16x32_bf16 v[20:23], v[196:199], v[148:151], v[20:23]
	v_mfma_f32_16x16x32_bf16 v[16:19], v[196:199], v[156:159], v[16:19]
	v_mfma_f32_16x16x32_bf16 v[4:7], v[214:217], v[148:151], v[4:7]
	v_mfma_f32_16x16x32_bf16 v[0:3], v[214:217], v[156:159], v[0:3]
	s_setprio 0
	s_barrier
	s_add_i32 s53, 0, 0x18000
	s_add_i32 s55, 0, 0x1c000
	v_add_u32_e32 v140, s53, v205
	v_add_u32_e32 v238, s53, v237
	v_add_u32_e32 v156, 0x19000, v205
	v_add_u32_e32 v239, 0x19000, v237
	ds_read_b128 v[128:131], v140
	ds_read_b128 v[132:135], v238
	ds_read_b128 v[136:139], v140 offset:2048
	ds_read_b128 v[140:143], v238 offset:2048
	ds_read_b128 v[144:147], v156
	ds_read_b128 v[148:151], v239
	ds_read_b128 v[152:155], v156 offset:2048
	ds_read_b128 v[156:159], v239 offset:2048
	s_add_u32 s66, s66, 0x80000
	s_addc_u32 s67, s67, 0
	s_mov_b32 m0, s15
	v_lshl_add_u64 v[226:227], s[66:67], 0, v[176:177]
	ds_read_b128 v[160:163], v210 offset:32768
	ds_read_b128 v[164:167], v234 offset:32768
	ds_read_b128 v[168:171], v210 offset:34816
	ds_read_b128 v[172:175], v234 offset:34816
	ds_read_b128 v[192:195], v210 offset:36864
	ds_read_b128 v[196:199], v234 offset:36864
	ds_read_b128 v[200:203], v210 offset:38912
	ds_read_b128 v[214:217], v234 offset:38912
	global_load_lds_dwordx4 v[226:227], off
	v_lshl_add_u64 v[226:227], s[66:67], 0, v[180:181]
	s_mov_b32 m0, s17
	s_nop 0
	global_load_lds_dwordx4 v[226:227], off
	s_waitcnt vmcnt(8)
	s_waitcnt lgkmcnt(0)
	s_barrier
	s_setprio 1
	s_waitcnt lgkmcnt(0)
	v_mfma_f32_16x16x32_bf16 v[124:127], v[160:163], v[128:131], v[124:127]
	v_mfma_f32_16x16x32_bf16 v[120:123], v[160:163], v[136:139], v[120:123]
	v_mfma_f32_16x16x32_bf16 v[108:111], v[168:171], v[128:131], v[108:111]
	v_mfma_f32_16x16x32_bf16 v[104:107], v[168:171], v[136:139], v[104:107]
	v_mfma_f32_16x16x32_bf16 v[92:95], v[192:195], v[128:131], v[92:95]
	v_mfma_f32_16x16x32_bf16 v[88:91], v[192:195], v[136:139], v[88:91]
	v_mfma_f32_16x16x32_bf16 v[76:79], v[200:203], v[128:131], v[76:79]
	v_mfma_f32_16x16x32_bf16 v[72:75], v[200:203], v[136:139], v[72:75]
	v_mfma_f32_16x16x32_bf16 v[124:127], v[164:167], v[132:135], v[124:127]
	v_mfma_f32_16x16x32_bf16 v[120:123], v[164:167], v[140:143], v[120:123]
	v_mfma_f32_16x16x32_bf16 v[108:111], v[172:175], v[132:135], v[108:111]
	v_mfma_f32_16x16x32_bf16 v[104:107], v[172:175], v[140:143], v[104:107]
	v_mfma_f32_16x16x32_bf16 v[92:95], v[196:199], v[132:135], v[92:95]
	v_mfma_f32_16x16x32_bf16 v[88:91], v[196:199], v[140:143], v[88:91]
	v_mfma_f32_16x16x32_bf16 v[76:79], v[214:217], v[132:135], v[76:79]
	v_mfma_f32_16x16x32_bf16 v[72:75], v[214:217], v[140:143], v[72:75]
	s_setprio 0
	s_setprio 1
	v_mfma_f32_16x16x32_bf16 v[116:119], v[160:163], v[144:147], v[116:119]
	v_mfma_f32_16x16x32_bf16 v[112:115], v[160:163], v[152:155], v[112:115]
	v_mfma_f32_16x16x32_bf16 v[100:103], v[168:171], v[144:147], v[100:103]
	v_mfma_f32_16x16x32_bf16 v[96:99], v[168:171], v[152:155], v[96:99]
	v_mfma_f32_16x16x32_bf16 v[84:87], v[192:195], v[144:147], v[84:87]
	v_mfma_f32_16x16x32_bf16 v[80:83], v[192:195], v[152:155], v[80:83]
	v_mfma_f32_16x16x32_bf16 v[68:71], v[200:203], v[144:147], v[68:71]
	v_mfma_f32_16x16x32_bf16 v[64:67], v[200:203], v[152:155], v[64:67]
	v_mfma_f32_16x16x32_bf16 v[116:119], v[164:167], v[148:151], v[116:119]
	v_mfma_f32_16x16x32_bf16 v[112:115], v[164:167], v[156:159], v[112:115]
	v_mfma_f32_16x16x32_bf16 v[100:103], v[172:175], v[148:151], v[100:103]
	v_mfma_f32_16x16x32_bf16 v[96:99], v[172:175], v[156:159], v[96:99]
	v_mfma_f32_16x16x32_bf16 v[84:87], v[196:199], v[148:151], v[84:87]
	v_mfma_f32_16x16x32_bf16 v[80:83], v[196:199], v[156:159], v[80:83]
	v_mfma_f32_16x16x32_bf16 v[68:71], v[214:217], v[148:151], v[68:71]
	v_mfma_f32_16x16x32_bf16 v[64:67], v[214:217], v[156:159], v[64:67]
	s_setprio 0
	s_barrier
; #define LAS __attribute__((address_space(3)))
; #define PG8_STAGE(bufoff, gbase, voff) do { _Pragma("unroll") for (int _i = 0; _i < 2; ++_i) \
;         __builtin_amdgcn_global_load_lds((const unsigned*)((const char*)(gbase) + (voff)[_i]), (LAS unsigned*)(lds + (bufoff) + ldsw + _i * 8192), 16, 0, 0); } while (0)
; #define PG8_LDA(dst, b, h) do { _Pragma("unroll") for (int m = 0; m < 4; ++m) _Pragma("unroll") for (int k = 0; k < 2; ++k) dst[m][k] = *(const LAS bf16x8*)(lds + PG8_SA(b, h) + aoff + m * 2048 + k * 1024); } while (0)
; #define PG8_WAIT_V(n) asm volatile("s_waitcnt vmcnt(" #n ")" ::: "memory")
; #define PG8_WAIT_L(n) asm volatile("s_waitcnt lgkmcnt(" #n ")" ::: "memory")
; #define PG8_BAR __builtin_amdgcn_s_barrier()
; template <class Epi, class Sched>
; __device__ __forceinline__ void gemm_phase(LAS unsigned char* lds, const int K, const int lda, const int ldb, const Sched& S, const Epi& E) {
;     ...
;             PG8_LDA(At, 1, 1); PG8_STAGE(PG8_SB(1, 0), b3, voffB); PG8_STAGE(PG8_SB(1, 1), b3 + hB, voffB); PG8_STAGE(PG8_SA(1, 0), a3, voffA);
;             PG8_WAIT_V(8); PG8_WAIT_L(0); PG8_BAR; PG8_MMA(1, 0, At, B0); PG8_MMA(1, 1, At, B1); PG8_BAR; PG8_SCHED;
;         }
;         if (wr == 0) PG8_BAR;
;     __device__ __forceinline__ void operator()(const f32x4 (&acc)[2][2][4][2], const Unit& u, int wr, int wc, int fr, int fq, LAS unsigned char* xs, int wid, int lane) const {
;         const int row0 = u.pm * 256 + wr * 64, col0 = u.pn * 256 + wc * 32 + 8 * fq;
;         const float* xo = (row0 < TP) ? xo_p : xo_s - (size_t)TP * D;
;         LAS float* P = (LAS float*)xs;
;         u32x4 raw[2][4][2];
;         if (!SRCF32) {
; #pragma unroll
;             for (int ai = 0; ai < 2; ++ai)
; #pragma unroll
;                 for (int m = 0; m < 4; ++m)
; #pragma unroll
;                     for (int bj = 0; bj < 2; ++bj) raw[ai][m][bj] = *(const u32x4*)(xb + (size_t)(row0 + ai * 128 + m * 16 + fr) * D + col0 + bj * 128);
;         }
; #pragma unroll
;         for (int ai = 0; ai < 2; ++ai) {
;             f32x4 xf[4][2][2];
;             if (SRCF32) {
; #pragma unroll
;                 for (int m = 0; m < 4; ++m)
; #pragma unroll
;                     for (int bj = 0; bj < 2; ++bj) { const size_t o = (size_t)(row0 + ai * 128 + m * 16 + fr) * D + col0 + bj * 128; xf[m][bj][0] = *(const f32x4*)(xo + o); xf[m][bj][1] = *(const f32x4*)(xo + o + 4); }
	s_add_i32 s53, s53, s1
	v_lshl_add_u64 v[218:219], v[218:219], 0, s[48:49]
	s_mov_b32 m0, s53
	ds_read_b128 v[160:163], v210 offset:49152
	ds_read_b128 v[164:167], v234 offset:49152
	ds_read_b128 v[168:171], v210 offset:51200
	ds_read_b128 v[172:175], v234 offset:51200
	ds_read_b128 v[192:195], v210 offset:53248
	ds_read_b128 v[196:199], v234 offset:53248
	ds_read_b128 v[200:203], v210 offset:55296
	ds_read_b128 v[214:217], v234 offset:55296
	global_load_lds_dwordx4 v[218:219], off
	s_add_i32 m0, s53, 0x2000
	s_add_u32 s64, s64, 0x80080
	v_lshl_add_u64 v[218:219], v[220:221], 0, s[48:49]
	s_addc_u32 s65, s65, 0
	s_add_i32 s53, s55, s1
	global_load_lds_dwordx4 v[218:219], off
	v_lshl_add_u64 v[218:219], s[64:65], 0, v[178:179]
	s_mov_b32 m0, s53
	s_nop 0
	global_load_lds_dwordx4 v[218:219], off
	v_lshl_add_u64 v[218:219], s[64:65], 0, v[182:183]
	s_add_i32 m0, s53, 0x2000
	s_nop 0
	global_load_lds_dwordx4 v[218:219], off
	v_lshl_add_u64 v[218:219], v[222:223], 0, s[48:49]
	s_mov_b32 m0, s0
	s_nop 0
	global_load_lds_dwordx4 v[218:219], off
	v_lshl_add_u64 v[218:219], v[224:225], 0, s[48:49]
	s_mov_b32 m0, s24
	s_nop 0
	global_load_lds_dwordx4 v[218:219], off
	s_waitcnt vmcnt(8)
	s_waitcnt lgkmcnt(0)
	s_barrier
	s_setprio 1
	s_waitcnt lgkmcnt(0)
	v_mfma_f32_16x16x32_bf16 v[60:63], v[160:163], v[128:131], v[60:63]
	v_mfma_f32_16x16x32_bf16 v[56:59], v[160:163], v[136:139], v[56:59]
	v_mfma_f32_16x16x32_bf16 v[44:47], v[168:171], v[128:131], v[44:47]
	v_mfma_f32_16x16x32_bf16 v[40:43], v[168:171], v[136:139], v[40:43]
	v_mfma_f32_16x16x32_bf16 v[28:31], v[192:195], v[128:131], v[28:31]
	v_mfma_f32_16x16x32_bf16 v[24:27], v[192:195], v[136:139], v[24:27]
	v_mfma_f32_16x16x32_bf16 v[12:15], v[200:203], v[128:131], v[12:15]
	v_mfma_f32_16x16x32_bf16 v[8:11], v[200:203], v[136:139], v[8:11]
	v_mfma_f32_16x16x32_bf16 v[60:63], v[164:167], v[132:135], v[60:63]
	v_mfma_f32_16x16x32_bf16 v[56:59], v[164:167], v[140:143], v[56:59]
	v_mfma_f32_16x16x32_bf16 v[44:47], v[172:175], v[132:135], v[44:47]
	v_mfma_f32_16x16x32_bf16 v[40:43], v[172:175], v[140:143], v[40:43]
	v_mfma_f32_16x16x32_bf16 v[28:31], v[196:199], v[132:135], v[28:31]
	v_mfma_f32_16x16x32_bf16 v[24:27], v[196:199], v[140:143], v[24:27]
	v_mfma_f32_16x16x32_bf16 v[12:15], v[214:217], v[132:135], v[12:15]
	v_mfma_f32_16x16x32_bf16 v[8:11], v[214:217], v[140:143], v[8:11]
	s_setprio 0
	s_setprio 1
	v_mfma_f32_16x16x32_bf16 v[52:55], v[160:163], v[144:147], v[52:55]
	v_mfma_f32_16x16x32_bf16 v[48:51], v[160:163], v[152:155], v[48:51]
	v_mfma_f32_16x16x32_bf16 v[36:39], v[168:171], v[144:147], v[36:39]
	v_mfma_f32_16x16x32_bf16 v[32:35], v[168:171], v[152:155], v[32:35]
	v_mfma_f32_16x16x32_bf16 v[20:23], v[192:195], v[144:147], v[20:23]
	v_mfma_f32_16x16x32_bf16 v[16:19], v[192:195], v[152:155], v[16:19]
	v_mfma_f32_16x16x32_bf16 v[4:7], v[200:203], v[144:147], v[4:7]
	v_mfma_f32_16x16x32_bf16 v[0:3], v[200:203], v[152:155], v[0:3]
	v_mfma_f32_16x16x32_bf16 v[52:55], v[164:167], v[148:151], v[52:55]
	v_mfma_f32_16x16x32_bf16 v[48:51], v[164:167], v[156:159], v[48:51]
	v_mfma_f32_16x16x32_bf16 v[36:39], v[172:175], v[148:151], v[36:39]
	v_mfma_f32_16x16x32_bf16 v[32:35], v[172:175], v[156:159], v[32:35]
	v_mfma_f32_16x16x32_bf16 v[20:23], v[196:199], v[148:151], v[20:23]
	v_mfma_f32_16x16x32_bf16 v[16:19], v[196:199], v[156:159], v[16:19]
	v_mfma_f32_16x16x32_bf16 v[4:7], v[214:217], v[148:151], v[4:7]
	v_mfma_f32_16x16x32_bf16 v[0:3], v[214:217], v[156:159], v[0:3]
	s_setprio 0
	s_barrier
	s_add_i32 s47, s47, 2
	s_add_u32 s39, s39, 0x100
	s_addc_u32 s41, s41, 0
	s_add_u32 s62, s62, 0x100
	s_addc_u32 s63, s63, 0
	s_cmp_gt_u32 s47, 29
	s_cbranch_scc0 .LBB0_619
	s_and_b64 vcc, exec, s[50:51]
	s_cbranch_vccz .LBB0_622
	s_barrier
.LBB0_622:
	v_readfirstlane_b32 s18, v254
	s_nop 1
	s_lshr_b32 s18, s18, 6
	s_lshr_b32 s19, s18, 2
	s_and_b32 s47, s18, 3
	s_lshl_b32 s41, s60, 8
	s_lshl_b32 s19, s19, 6
	s_add_i32 s32, s41, s19
	s_lshl_b32 s35, s46, 8
	s_lshl_b32 s18, s47, 6
	s_add_i32 s35, s35, s18
	s_lshl_b32 s32, s32, 11
	s_add_i32 s32, s32, s35
	s_lshl_b32 s35, s32, 1
	s_add_u32 s38, s12, s35
	s_addc_u32 s39, s13, 0
	v_and_b32_e32 v130, 15, v254
	v_bfe_u32 v132, v254, 4, 2
	v_lshlrev_b32_e32 v128, 13, v132
	v_lshl_add_u32 v128, v130, 2, v128
	v_lshlrev_b32_e32 v138, 2, v128
	v_lshlrev_b32_e32 v128, 1, v128
	s_lshr_b32 s18, s32, 11
	s_cmpk_lt_i32 s18, 0x4000
	s_cselect_b32 s66, s44, s27
	s_cselect_b32 s67, s45, s28
	s_lshl_b32 s18, s32, 2
	s_add_u32 s66, s66, s18
	s_addc_u32 s67, s67, 0
	v_lshlrev_b32_e32 v137, 6, v132
	v_add_u32_e32 v137, 0x20000, v137
	s_lshl_b32 s19, s19, 4
	s_lshl_b32 s18, s47, 2
	s_add_i32 s19, s19, s18
	v_add_u32_e32 v137, s19, v137
	s_add_u32 s62, s66, 0x0
	s_addc_u32 s63, s67, 0
	global_load_dwordx4 v[140:143], v138, s[62:63]
	s_add_u32 s64, s66, 0x2000
	s_addc_u32 s65, s67, 0
	global_load_dwordx4 v[144:147], v138, s[64:65]
	s_add_u32 s62, s66, 0x4000
	s_addc_u32 s63, s67, 0
	global_load_dwordx4 v[148:151], v138, s[62:63]
	s_add_u32 s64, s66, 0x6000
	s_addc_u32 s65, s67, 0
	global_load_dwordx4 v[152:155], v138, s[64:65]
	s_add_u32 s62, s66, 0x20000
	s_addc_u32 s63, s67, 0
	global_load_dwordx4 v[156:159], v138, s[62:63]
	s_add_u32 s64, s66, 0x22000
	s_addc_u32 s65, s67, 0
	global_load_dwordx4 v[160:163], v138, s[64:65]
	s_add_u32 s62, s66, 0x24000
	s_addc_u32 s63, s67, 0
	global_load_dwordx4 v[164:167], v138, s[62:63]
	s_add_u32 s64, s66, 0x26000
	s_addc_u32 s65, s67, 0
	global_load_dwordx4 v[168:171], v138, s[64:65]
	s_waitcnt vmcnt(7)
; __device__ __forceinline__ unsigned cvt_pk_bf16(float lo, float hi) { unsigned r; asm("v_cvt_pk_bf16_f32 %0, %1, %2" : "=v"(r) : "v"(lo), "v"(hi)); return r; }
;     __device__ __forceinline__ void operator()(const f32x4 (&acc)[2][2][4][2], const Unit& u, int wr, int wc, int fr, int fq, LAS unsigned char* xs, int wid, int lane) const {
;     ...
;             if (SRCF32) {
; #pragma unroll
;                 for (int m = 0; m < 4; ++m)
; #pragma unroll
;                     for (int bj = 0; bj < 2; ++bj) { const size_t o = (size_t)(row0 + ai * 128 + m * 16 + fr) * D + col0 + bj * 128; xf[m][bj][0] = *(const f32x4*)(xo + o); xf[m][bj][1] = *(const f32x4*)(xo + o + 4); }
;             }
; #pragma unroll
;             for (int m = 0; m < 4; ++m) {
;                 const size_t row = (size_t)(row0 + ai * 128 + m * 16 + fr);
;                 float ss = 0.f;
; #pragma unroll
;                 for (int bj = 0; bj < 2; ++bj) {
;                     const size_t o = row * D + col0 + bj * 128;
;                     f32x4 x0, x1;
;                     if (SRCF32) { x0 = xf[m][bj][0]; x1 = xf[m][bj][1]; }
;                     else { const u32x4 r = raw[ai][m][bj]; x0 = (f32x4){bf_lo(r.x), bf_hi(r.x), bf_lo(r.y), bf_hi(r.y)}; x1 = (f32x4){bf_lo(r.z), bf_hi(r.z), bf_lo(r.w), bf_hi(r.w)}; }
;                     const f32x4 v0 = x0 + acc[ai][bj][m][0], v1 = x1 + acc[ai][bj][m][1];
;                     if (LAST) { *(f32x4*)(out + o) = v0; *(f32x4*)(out + o + 4) = v1; }
;                     else {
;                         ss += (v0[0] * v0[0] + v0[1] * v0[1]) + (v0[2] * v0[2] + v0[3] * v0[3]) + (v1[0] * v1[0] + v1[1] * v1[1]) + (v1[2] * v1[2] + v1[3] * v1[3]);
;                         u32x4 w; w.x = cvt_pk_bf16(v0[0], v0[1]); w.y = cvt_pk_bf16(v0[2], v0[3]); w.z = cvt_pk_bf16(v1[0], v1[1]); w.w = cvt_pk_bf16(v1[2], v1[3]); *(u32x4*)(xb + o) = w;
	v_add_f32_e32 v124, v124, v140
	v_add_f32_e32 v120, v120, v141
	v_add_f32_e32 v116, v116, v142
	v_add_f32_e32 v112, v112, v143
	v_cvt_pk_bf16_f32 v224, v124, v120
	v_cvt_pk_bf16_f32 v225, v116, v112
	v_mul_f32_e32 v124, v124, v124
	v_fmac_f32_e32 v124, v120, v120
	v_fmac_f32_e32 v124, v116, v116
	v_fmac_f32_e32 v124, v112, v112
	s_add_u32 s62, s38, 0x0
	s_addc_u32 s63, s39, 0
	global_store_dwordx2 v128, v[224:225], s[62:63]
	s_waitcnt vmcnt(7)
	v_add_f32_e32 v125, v125, v144
	v_add_f32_e32 v121, v121, v145
	v_add_f32_e32 v117, v117, v146
	v_add_f32_e32 v113, v113, v147
	v_cvt_pk_bf16_f32 v226, v125, v121
	v_cvt_pk_bf16_f32 v227, v117, v113
	v_mul_f32_e32 v125, v125, v125
	v_fmac_f32_e32 v125, v121, v121
	v_fmac_f32_e32 v125, v117, v117
	v_fmac_f32_e32 v125, v113, v113
	s_add_u32 s64, s38, 0x1000
	s_addc_u32 s65, s39, 0
	global_store_dwordx2 v128, v[226:227], s[64:65]
	s_waitcnt vmcnt(7)
	v_add_f32_e32 v126, v126, v148
	v_add_f32_e32 v122, v122, v149
	v_add_f32_e32 v118, v118, v150
	v_add_f32_e32 v114, v114, v151
	v_cvt_pk_bf16_f32 v228, v126, v122
	v_cvt_pk_bf16_f32 v229, v118, v114
	v_mul_f32_e32 v126, v126, v126
	v_fmac_f32_e32 v126, v122, v122
	v_fmac_f32_e32 v126, v118, v118
	v_fmac_f32_e32 v126, v114, v114
	s_add_u32 s62, s38, 0x2000
	s_addc_u32 s63, s39, 0
	global_store_dwordx2 v128, v[228:229], s[62:63]
	s_waitcnt vmcnt(7)
	v_add_f32_e32 v127, v127, v152
	v_add_f32_e32 v123, v123, v153
	v_add_f32_e32 v119, v119, v154
	v_add_f32_e32 v115, v115, v155
	v_cvt_pk_bf16_f32 v230, v127, v123
	v_cvt_pk_bf16_f32 v231, v119, v115
	v_mul_f32_e32 v127, v127, v127
	v_fmac_f32_e32 v127, v123, v123
	v_fmac_f32_e32 v127, v119, v119
	v_fmac_f32_e32 v127, v115, v115
	s_add_u32 s64, s38, 0x3000
	s_addc_u32 s65, s39, 0
	global_store_dwordx2 v128, v[230:231], s[64:65]
	s_waitcnt vmcnt(7)
	v_add_f32_e32 v108, v108, v156
	v_add_f32_e32 v104, v104, v157
	v_add_f32_e32 v100, v100, v158
	v_add_f32_e32 v96, v96, v159
	v_cvt_pk_bf16_f32 v224, v108, v104
	v_cvt_pk_bf16_f32 v225, v100, v96
	v_mul_f32_e32 v108, v108, v108
	v_fmac_f32_e32 v108, v104, v104
	v_fmac_f32_e32 v108, v100, v100
	v_fmac_f32_e32 v108, v96, v96
	s_add_u32 s62, s38, 0x10000
	s_addc_u32 s63, s39, 0
	global_store_dwordx2 v128, v[224:225], s[62:63]
	s_waitcnt vmcnt(7)
	v_add_f32_e32 v109, v109, v160
	v_add_f32_e32 v105, v105, v161
	v_add_f32_e32 v101, v101, v162
	v_add_f32_e32 v97, v97, v163
	v_cvt_pk_bf16_f32 v226, v109, v105
	v_cvt_pk_bf16_f32 v227, v101, v97
	v_mul_f32_e32 v109, v109, v109
	v_fmac_f32_e32 v109, v105, v105
	v_fmac_f32_e32 v109, v101, v101
	v_fmac_f32_e32 v109, v97, v97
	s_add_u32 s64, s38, 0x11000
	s_addc_u32 s65, s39, 0
	global_store_dwordx2 v128, v[226:227], s[64:65]
	s_waitcnt vmcnt(7)
	v_add_f32_e32 v110, v110, v164
	v_add_f32_e32 v106, v106, v165
	v_add_f32_e32 v102, v102, v166
	v_add_f32_e32 v98, v98, v167
	v_cvt_pk_bf16_f32 v228, v110, v106
	v_cvt_pk_bf16_f32 v229, v102, v98
	v_mul_f32_e32 v110, v110, v110
	v_fmac_f32_e32 v110, v106, v106
	v_fmac_f32_e32 v110, v102, v102
	v_fmac_f32_e32 v110, v98, v98
	s_add_u32 s62, s38, 0x12000
	s_addc_u32 s63, s39, 0
	global_store_dwordx2 v128, v[228:229], s[62:63]
	s_waitcnt vmcnt(7)
	v_add_f32_e32 v111, v111, v168
	v_add_f32_e32 v107, v107, v169
	v_add_f32_e32 v103, v103, v170
	v_add_f32_e32 v99, v99, v171
	v_cvt_pk_bf16_f32 v230, v111, v107
	v_cvt_pk_bf16_f32 v231, v103, v99
	v_mul_f32_e32 v111, v111, v111
	v_fmac_f32_e32 v111, v107, v107
	v_fmac_f32_e32 v111, v103, v103
	v_fmac_f32_e32 v111, v99, v99
	s_add_u32 s64, s38, 0x13000
	s_addc_u32 s65, s39, 0
	global_store_dwordx2 v128, v[230:231], s[64:65]
	s_add_u32 s62, s66, 0x40000
	s_addc_u32 s63, s67, 0
	global_load_dwordx4 v[140:143], v138, s[62:63]
	s_add_u32 s64, s66, 0x42000
	s_addc_u32 s65, s67, 0
	global_load_dwordx4 v[144:147], v138, s[64:65]
	s_add_u32 s62, s66, 0x44000
	s_addc_u32 s63, s67, 0
	global_load_dwordx4 v[148:151], v138, s[62:63]
	s_add_u32 s64, s66, 0x46000
	s_addc_u32 s65, s67, 0
	global_load_dwordx4 v[152:155], v138, s[64:65]
	s_add_u32 s62, s66, 0x60000
	s_addc_u32 s63, s67, 0
	global_load_dwordx4 v[156:159], v138, s[62:63]
	s_add_u32 s64, s66, 0x62000
	s_addc_u32 s65, s67, 0
	global_load_dwordx4 v[160:163], v138, s[64:65]
	s_add_u32 s62, s66, 0x64000
	s_addc_u32 s63, s67, 0
	global_load_dwordx4 v[164:167], v138, s[62:63]
	s_add_u32 s64, s66, 0x66000
	s_addc_u32 s65, s67, 0
	global_load_dwordx4 v[168:171], v138, s[64:65]
	s_waitcnt vmcnt(7)
	v_add_f32_e32 v92, v92, v140
	v_add_f32_e32 v88, v88, v141
	v_add_f32_e32 v84, v84, v142
	v_add_f32_e32 v80, v80, v143
	v_cvt_pk_bf16_f32 v224, v92, v88
	v_cvt_pk_bf16_f32 v225, v84, v80
	v_mul_f32_e32 v92, v92, v92
	v_fmac_f32_e32 v92, v88, v88
	v_fmac_f32_e32 v92, v84, v84
	v_fmac_f32_e32 v92, v80, v80
	s_add_u32 s62, s38, 0x20000
	s_addc_u32 s63, s39, 0
	global_store_dwordx2 v128, v[224:225], s[62:63]
	s_waitcnt vmcnt(7)
	v_add_f32_e32 v93, v93, v144
	v_add_f32_e32 v89, v89, v145
	v_add_f32_e32 v85, v85, v146
	v_add_f32_e32 v81, v81, v147
	v_cvt_pk_bf16_f32 v226, v93, v89
	v_cvt_pk_bf16_f32 v227, v85, v81
	v_mul_f32_e32 v93, v93, v93
	v_fmac_f32_e32 v93, v89, v89
	v_fmac_f32_e32 v93, v85, v85
	v_fmac_f32_e32 v93, v81, v81
	s_add_u32 s64, s38, 0x21000
	s_addc_u32 s65, s39, 0
	global_store_dwordx2 v128, v[226:227], s[64:65]
	s_waitcnt vmcnt(7)
	v_add_f32_e32 v94, v94, v148
	v_add_f32_e32 v90, v90, v149
	v_add_f32_e32 v86, v86, v150
	v_add_f32_e32 v82, v82, v151
	v_cvt_pk_bf16_f32 v228, v94, v90
	v_cvt_pk_bf16_f32 v229, v86, v82
	v_mul_f32_e32 v94, v94, v94
	v_fmac_f32_e32 v94, v90, v90
	v_fmac_f32_e32 v94, v86, v86
	v_fmac_f32_e32 v94, v82, v82
	s_add_u32 s62, s38, 0x22000
	s_addc_u32 s63, s39, 0
	global_store_dwordx2 v128, v[228:229], s[62:63]
	s_waitcnt vmcnt(7)
; __device__ __forceinline__ unsigned cvt_pk_bf16(float lo, float hi) { unsigned r; asm("v_cvt_pk_bf16_f32 %0, %1, %2" : "=v"(r) : "v"(lo), "v"(hi)); return r; }
;     __device__ __forceinline__ void operator()(const f32x4 (&acc)[2][2][4][2], const Unit& u, int wr, int wc, int fr, int fq, LAS unsigned char* xs, int wid, int lane) const {
;     ...
;             if (SRCF32) {
; #pragma unroll
;                 for (int m = 0; m < 4; ++m)
; #pragma unroll
;                     for (int bj = 0; bj < 2; ++bj) { const size_t o = (size_t)(row0 + ai * 128 + m * 16 + fr) * D + col0 + bj * 128; xf[m][bj][0] = *(const f32x4*)(xo + o); xf[m][bj][1] = *(const f32x4*)(xo + o + 4); }
;             }
; #pragma unroll
;             for (int m = 0; m < 4; ++m) {
;                 const size_t row = (size_t)(row0 + ai * 128 + m * 16 + fr);
;                 float ss = 0.f;
; #pragma unroll
;                 for (int bj = 0; bj < 2; ++bj) {
;                     const size_t o = row * D + col0 + bj * 128;
;                     f32x4 x0, x1;
;                     if (SRCF32) { x0 = xf[m][bj][0]; x1 = xf[m][bj][1]; }
;                     else { const u32x4 r = raw[ai][m][bj]; x0 = (f32x4){bf_lo(r.x), bf_hi(r.x), bf_lo(r.y), bf_hi(r.y)}; x1 = (f32x4){bf_lo(r.z), bf_hi(r.z), bf_lo(r.w), bf_hi(r.w)}; }
;                     const f32x4 v0 = x0 + acc[ai][bj][m][0], v1 = x1 + acc[ai][bj][m][1];
;                     if (LAST) { *(f32x4*)(out + o) = v0; *(f32x4*)(out + o + 4) = v1; }
;                     else {
;                         ss += (v0[0] * v0[0] + v0[1] * v0[1]) + (v0[2] * v0[2] + v0[3] * v0[3]) + (v1[0] * v1[0] + v1[1] * v1[1]) + (v1[2] * v1[2] + v1[3] * v1[3]);
;                         u32x4 w; w.x = cvt_pk_bf16(v0[0], v0[1]); w.y = cvt_pk_bf16(v0[2], v0[3]); w.z = cvt_pk_bf16(v1[0], v1[1]); w.w = cvt_pk_bf16(v1[2], v1[3]); *(u32x4*)(xb + o) = w;
	v_add_f32_e32 v95, v95, v152
	v_add_f32_e32 v91, v91, v153
	v_add_f32_e32 v87, v87, v154
	v_add_f32_e32 v83, v83, v155
	v_cvt_pk_bf16_f32 v230, v95, v91
	v_cvt_pk_bf16_f32 v231, v87, v83
	v_mul_f32_e32 v95, v95, v95
	v_fmac_f32_e32 v95, v91, v91
	v_fmac_f32_e32 v95, v87, v87
	v_fmac_f32_e32 v95, v83, v83
	s_add_u32 s64, s38, 0x23000
	s_addc_u32 s65, s39, 0
	global_store_dwordx2 v128, v[230:231], s[64:65]
	s_waitcnt vmcnt(7)
	v_add_f32_e32 v76, v76, v156
	v_add_f32_e32 v72, v72, v157
	v_add_f32_e32 v68, v68, v158
	v_add_f32_e32 v64, v64, v159
	v_cvt_pk_bf16_f32 v224, v76, v72
	v_cvt_pk_bf16_f32 v225, v68, v64
	v_mul_f32_e32 v76, v76, v76
	v_fmac_f32_e32 v76, v72, v72
	v_fmac_f32_e32 v76, v68, v68
	v_fmac_f32_e32 v76, v64, v64
	s_add_u32 s62, s38, 0x30000
	s_addc_u32 s63, s39, 0
	global_store_dwordx2 v128, v[224:225], s[62:63]
	s_waitcnt vmcnt(7)
	v_add_f32_e32 v77, v77, v160
	v_add_f32_e32 v73, v73, v161
	v_add_f32_e32 v69, v69, v162
	v_add_f32_e32 v65, v65, v163
	v_cvt_pk_bf16_f32 v226, v77, v73
	v_cvt_pk_bf16_f32 v227, v69, v65
	v_mul_f32_e32 v77, v77, v77
	v_fmac_f32_e32 v77, v73, v73
	v_fmac_f32_e32 v77, v69, v69
	v_fmac_f32_e32 v77, v65, v65
	s_add_u32 s64, s38, 0x31000
	s_addc_u32 s65, s39, 0
	global_store_dwordx2 v128, v[226:227], s[64:65]
	s_waitcnt vmcnt(7)
	v_add_f32_e32 v78, v78, v164
	v_add_f32_e32 v74, v74, v165
	v_add_f32_e32 v70, v70, v166
	v_add_f32_e32 v66, v66, v167
	v_cvt_pk_bf16_f32 v228, v78, v74
	v_cvt_pk_bf16_f32 v229, v70, v66
	v_mul_f32_e32 v78, v78, v78
	v_fmac_f32_e32 v78, v74, v74
	v_fmac_f32_e32 v78, v70, v70
	v_fmac_f32_e32 v78, v66, v66
	s_add_u32 s62, s38, 0x32000
	s_addc_u32 s63, s39, 0
	global_store_dwordx2 v128, v[228:229], s[62:63]
	s_waitcnt vmcnt(7)
	v_add_f32_e32 v79, v79, v168
	v_add_f32_e32 v75, v75, v169
	v_add_f32_e32 v71, v71, v170
	v_add_f32_e32 v67, v67, v171
	v_cvt_pk_bf16_f32 v230, v79, v75
	v_cvt_pk_bf16_f32 v231, v71, v67
	v_mul_f32_e32 v79, v79, v79
	v_fmac_f32_e32 v79, v75, v75
	v_fmac_f32_e32 v79, v71, v71
	v_fmac_f32_e32 v79, v67, v67
	s_add_u32 s64, s38, 0x33000
	s_addc_u32 s65, s39, 0
	global_store_dwordx2 v128, v[230:231], s[64:65]
	s_add_u32 s62, s66, 0x100000
	s_addc_u32 s63, s67, 0
	global_load_dwordx4 v[140:143], v138, s[62:63]
	s_add_u32 s64, s66, 0x102000
	s_addc_u32 s65, s67, 0
	global_load_dwordx4 v[144:147], v138, s[64:65]
	s_add_u32 s62, s66, 0x104000
	s_addc_u32 s63, s67, 0
	global_load_dwordx4 v[148:151], v138, s[62:63]
	s_add_u32 s64, s66, 0x106000
	s_addc_u32 s65, s67, 0
	global_load_dwordx4 v[152:155], v138, s[64:65]
	s_add_u32 s62, s66, 0x120000
	s_addc_u32 s63, s67, 0
	global_load_dwordx4 v[156:159], v138, s[62:63]
	s_add_u32 s64, s66, 0x122000
	s_addc_u32 s65, s67, 0
	global_load_dwordx4 v[160:163], v138, s[64:65]
	s_add_u32 s62, s66, 0x124000
	s_addc_u32 s63, s67, 0
	global_load_dwordx4 v[164:167], v138, s[62:63]
	s_add_u32 s64, s66, 0x126000
	s_addc_u32 s65, s67, 0
	global_load_dwordx4 v[168:171], v138, s[64:65]
	s_waitcnt vmcnt(7)
	v_add_f32_e32 v60, v60, v140
	v_add_f32_e32 v56, v56, v141
	v_add_f32_e32 v52, v52, v142
	v_add_f32_e32 v48, v48, v143
	v_cvt_pk_bf16_f32 v224, v60, v56
	v_cvt_pk_bf16_f32 v225, v52, v48
	v_mul_f32_e32 v60, v60, v60
	v_fmac_f32_e32 v60, v56, v56
	v_fmac_f32_e32 v60, v52, v52
	v_fmac_f32_e32 v60, v48, v48
	s_add_u32 s62, s38, 0x80000
	s_addc_u32 s63, s39, 0
	global_store_dwordx2 v128, v[224:225], s[62:63]
	s_waitcnt vmcnt(7)
	v_add_f32_e32 v61, v61, v144
	v_add_f32_e32 v57, v57, v145
	v_add_f32_e32 v53, v53, v146
	v_add_f32_e32 v49, v49, v147
	v_cvt_pk_bf16_f32 v226, v61, v57
	v_cvt_pk_bf16_f32 v227, v53, v49
	v_mul_f32_e32 v61, v61, v61
	v_fmac_f32_e32 v61, v57, v57
	v_fmac_f32_e32 v61, v53, v53
	v_fmac_f32_e32 v61, v49, v49
	s_add_u32 s64, s38, 0x81000
	s_addc_u32 s65, s39, 0
	global_store_dwordx2 v128, v[226:227], s[64:65]
	s_waitcnt vmcnt(7)
	v_add_f32_e32 v62, v62, v148
	v_add_f32_e32 v58, v58, v149
	v_add_f32_e32 v54, v54, v150
	v_add_f32_e32 v50, v50, v151
	v_cvt_pk_bf16_f32 v228, v62, v58
	v_cvt_pk_bf16_f32 v229, v54, v50
	v_mul_f32_e32 v62, v62, v62
	v_fmac_f32_e32 v62, v58, v58
	v_fmac_f32_e32 v62, v54, v54
	v_fmac_f32_e32 v62, v50, v50
	s_add_u32 s62, s38, 0x82000
	s_addc_u32 s63, s39, 0
	global_store_dwordx2 v128, v[228:229], s[62:63]
	s_waitcnt vmcnt(7)
	v_add_f32_e32 v63, v63, v152
	v_add_f32_e32 v59, v59, v153
	v_add_f32_e32 v55, v55, v154
	v_add_f32_e32 v51, v51, v155
	v_cvt_pk_bf16_f32 v230, v63, v59
	v_cvt_pk_bf16_f32 v231, v55, v51
	v_mul_f32_e32 v63, v63, v63
	v_fmac_f32_e32 v63, v59, v59
	v_fmac_f32_e32 v63, v55, v55
	v_fmac_f32_e32 v63, v51, v51
	s_add_u32 s64, s38, 0x83000
	s_addc_u32 s65, s39, 0
	global_store_dwordx2 v128, v[230:231], s[64:65]
	s_waitcnt vmcnt(7)
	v_add_f32_e32 v44, v44, v156
	v_add_f32_e32 v40, v40, v157
	v_add_f32_e32 v36, v36, v158
	v_add_f32_e32 v32, v32, v159
	v_cvt_pk_bf16_f32 v224, v44, v40
	v_cvt_pk_bf16_f32 v225, v36, v32
	v_mul_f32_e32 v44, v44, v44
	v_fmac_f32_e32 v44, v40, v40
	v_fmac_f32_e32 v44, v36, v36
	v_fmac_f32_e32 v44, v32, v32
	s_add_u32 s62, s38, 0x90000
	s_addc_u32 s63, s39, 0
	global_store_dwordx2 v128, v[224:225], s[62:63]
	s_waitcnt vmcnt(7)
	v_add_f32_e32 v45, v45, v160
	v_add_f32_e32 v41, v41, v161
	v_add_f32_e32 v37, v37, v162
	v_add_f32_e32 v33, v33, v163
	v_cvt_pk_bf16_f32 v226, v45, v41
	v_cvt_pk_bf16_f32 v227, v37, v33
	v_mul_f32_e32 v45, v45, v45
	v_fmac_f32_e32 v45, v41, v41
	v_fmac_f32_e32 v45, v37, v37
	v_fmac_f32_e32 v45, v33, v33
	s_add_u32 s64, s38, 0x91000
	s_addc_u32 s65, s39, 0
	global_store_dwordx2 v128, v[226:227], s[64:65]
	s_waitcnt vmcnt(7)
; __device__ __forceinline__ unsigned cvt_pk_bf16(float lo, float hi) { unsigned r; asm("v_cvt_pk_bf16_f32 %0, %1, %2" : "=v"(r) : "v"(lo), "v"(hi)); return r; }
;     __device__ __forceinline__ void operator()(const f32x4 (&acc)[2][2][4][2], const Unit& u, int wr, int wc, int fr, int fq, LAS unsigned char* xs, int wid, int lane) const {
;     ...
;             if (SRCF32) {
; #pragma unroll
;                 for (int m = 0; m < 4; ++m)
; #pragma unroll
;                     for (int bj = 0; bj < 2; ++bj) { const size_t o = (size_t)(row0 + ai * 128 + m * 16 + fr) * D + col0 + bj * 128; xf[m][bj][0] = *(const f32x4*)(xo + o); xf[m][bj][1] = *(const f32x4*)(xo + o + 4); }
;             }
; #pragma unroll
;             for (int m = 0; m < 4; ++m) {
;                 const size_t row = (size_t)(row0 + ai * 128 + m * 16 + fr);
;                 float ss = 0.f;
; #pragma unroll
;                 for (int bj = 0; bj < 2; ++bj) {
;                     const size_t o = row * D + col0 + bj * 128;
;                     f32x4 x0, x1;
;                     if (SRCF32) { x0 = xf[m][bj][0]; x1 = xf[m][bj][1]; }
;                     else { const u32x4 r = raw[ai][m][bj]; x0 = (f32x4){bf_lo(r.x), bf_hi(r.x), bf_lo(r.y), bf_hi(r.y)}; x1 = (f32x4){bf_lo(r.z), bf_hi(r.z), bf_lo(r.w), bf_hi(r.w)}; }
;                     const f32x4 v0 = x0 + acc[ai][bj][m][0], v1 = x1 + acc[ai][bj][m][1];
;                     if (LAST) { *(f32x4*)(out + o) = v0; *(f32x4*)(out + o + 4) = v1; }
;                     else {
;                         ss += (v0[0] * v0[0] + v0[1] * v0[1]) + (v0[2] * v0[2] + v0[3] * v0[3]) + (v1[0] * v1[0] + v1[1] * v1[1]) + (v1[2] * v1[2] + v1[3] * v1[3]);
;                         u32x4 w; w.x = cvt_pk_bf16(v0[0], v0[1]); w.y = cvt_pk_bf16(v0[2], v0[3]); w.z = cvt_pk_bf16(v1[0], v1[1]); w.w = cvt_pk_bf16(v1[2], v1[3]); *(u32x4*)(xb + o) = w;
	v_add_f32_e32 v46, v46, v164
	v_add_f32_e32 v42, v42, v165
	v_add_f32_e32 v38, v38, v166
	v_add_f32_e32 v34, v34, v167
	v_cvt_pk_bf16_f32 v228, v46, v42
	v_cvt_pk_bf16_f32 v229, v38, v34
	v_mul_f32_e32 v46, v46, v46
	v_fmac_f32_e32 v46, v42, v42
	v_fmac_f32_e32 v46, v38, v38
	v_fmac_f32_e32 v46, v34, v34
	s_add_u32 s62, s38, 0x92000
	s_addc_u32 s63, s39, 0
	global_store_dwordx2 v128, v[228:229], s[62:63]
	s_waitcnt vmcnt(7)
	v_add_f32_e32 v47, v47, v168
	v_add_f32_e32 v43, v43, v169
	v_add_f32_e32 v39, v39, v170
	v_add_f32_e32 v35, v35, v171
	v_cvt_pk_bf16_f32 v230, v47, v43
	v_cvt_pk_bf16_f32 v231, v39, v35
	v_mul_f32_e32 v47, v47, v47
	v_fmac_f32_e32 v47, v43, v43
	v_fmac_f32_e32 v47, v39, v39
	v_fmac_f32_e32 v47, v35, v35
	s_add_u32 s64, s38, 0x93000
	s_addc_u32 s65, s39, 0
	global_store_dwordx2 v128, v[230:231], s[64:65]
	s_add_u32 s62, s66, 0x140000
	s_addc_u32 s63, s67, 0
	global_load_dwordx4 v[140:143], v138, s[62:63]
	s_add_u32 s64, s66, 0x142000
	s_addc_u32 s65, s67, 0
	global_load_dwordx4 v[144:147], v138, s[64:65]
	s_add_u32 s62, s66, 0x144000
	s_addc_u32 s63, s67, 0
	global_load_dwordx4 v[148:151], v138, s[62:63]
	s_add_u32 s64, s66, 0x146000
	s_addc_u32 s65, s67, 0
	global_load_dwordx4 v[152:155], v138, s[64:65]
	s_add_u32 s62, s66, 0x160000
	s_addc_u32 s63, s67, 0
	global_load_dwordx4 v[156:159], v138, s[62:63]
	s_add_u32 s64, s66, 0x162000
	s_addc_u32 s65, s67, 0
	global_load_dwordx4 v[160:163], v138, s[64:65]
	s_add_u32 s62, s66, 0x164000
	s_addc_u32 s63, s67, 0
	global_load_dwordx4 v[164:167], v138, s[62:63]
	s_add_u32 s64, s66, 0x166000
	s_addc_u32 s65, s67, 0
	global_load_dwordx4 v[168:171], v138, s[64:65]
	s_waitcnt vmcnt(7)
	v_add_f32_e32 v28, v28, v140
	v_add_f32_e32 v24, v24, v141
	v_add_f32_e32 v20, v20, v142
	v_add_f32_e32 v16, v16, v143
	v_cvt_pk_bf16_f32 v224, v28, v24
	v_cvt_pk_bf16_f32 v225, v20, v16
	v_mul_f32_e32 v28, v28, v28
	v_fmac_f32_e32 v28, v24, v24
	v_fmac_f32_e32 v28, v20, v20
	v_fmac_f32_e32 v28, v16, v16
	s_add_u32 s62, s38, 0xa0000
	s_addc_u32 s63, s39, 0
	global_store_dwordx2 v128, v[224:225], s[62:63]
	s_waitcnt vmcnt(7)
	v_add_f32_e32 v29, v29, v144
	v_add_f32_e32 v25, v25, v145
	v_add_f32_e32 v21, v21, v146
	v_add_f32_e32 v17, v17, v147
	v_cvt_pk_bf16_f32 v226, v29, v25
	v_cvt_pk_bf16_f32 v227, v21, v17
	v_mul_f32_e32 v29, v29, v29
	v_fmac_f32_e32 v29, v25, v25
	v_fmac_f32_e32 v29, v21, v21
	v_fmac_f32_e32 v29, v17, v17
	s_add_u32 s64, s38, 0xa1000
	s_addc_u32 s65, s39, 0
	global_store_dwordx2 v128, v[226:227], s[64:65]
	s_waitcnt vmcnt(7)
	v_add_f32_e32 v30, v30, v148
	v_add_f32_e32 v26, v26, v149
	v_add_f32_e32 v22, v22, v150
	v_add_f32_e32 v18, v18, v151
	v_cvt_pk_bf16_f32 v228, v30, v26
	v_cvt_pk_bf16_f32 v229, v22, v18
	v_mul_f32_e32 v30, v30, v30
	v_fmac_f32_e32 v30, v26, v26
	v_fmac_f32_e32 v30, v22, v22
	v_fmac_f32_e32 v30, v18, v18
	s_add_u32 s62, s38, 0xa2000
	s_addc_u32 s63, s39, 0
	global_store_dwordx2 v128, v[228:229], s[62:63]
	s_waitcnt vmcnt(7)
	v_add_f32_e32 v31, v31, v152
	v_add_f32_e32 v27, v27, v153
	v_add_f32_e32 v23, v23, v154
	v_add_f32_e32 v19, v19, v155
	v_cvt_pk_bf16_f32 v230, v31, v27
	v_cvt_pk_bf16_f32 v231, v23, v19
	v_mul_f32_e32 v31, v31, v31
	v_fmac_f32_e32 v31, v27, v27
	v_fmac_f32_e32 v31, v23, v23
	v_fmac_f32_e32 v31, v19, v19
	s_add_u32 s64, s38, 0xa3000
	s_addc_u32 s65, s39, 0
	global_store_dwordx2 v128, v[230:231], s[64:65]
	s_waitcnt vmcnt(7)
	v_add_f32_e32 v12, v12, v156
	v_add_f32_e32 v8, v8, v157
	v_add_f32_e32 v4, v4, v158
	v_add_f32_e32 v0, v0, v159
	v_cvt_pk_bf16_f32 v224, v12, v8
	v_cvt_pk_bf16_f32 v225, v4, v0
	v_mul_f32_e32 v12, v12, v12
	v_fmac_f32_e32 v12, v8, v8
	v_fmac_f32_e32 v12, v4, v4
	v_fmac_f32_e32 v12, v0, v0
	s_add_u32 s62, s38, 0xb0000
	s_addc_u32 s63, s39, 0
	global_store_dwordx2 v128, v[224:225], s[62:63]
	s_waitcnt vmcnt(7)
	v_add_f32_e32 v13, v13, v160
	v_add_f32_e32 v9, v9, v161
	v_add_f32_e32 v5, v5, v162
	v_add_f32_e32 v1, v1, v163
	v_cvt_pk_bf16_f32 v226, v13, v9
	v_cvt_pk_bf16_f32 v227, v5, v1
	v_mul_f32_e32 v13, v13, v13
	v_fmac_f32_e32 v13, v9, v9
	v_fmac_f32_e32 v13, v5, v5
	v_fmac_f32_e32 v13, v1, v1
	s_add_u32 s64, s38, 0xb1000
	s_addc_u32 s65, s39, 0
	global_store_dwordx2 v128, v[226:227], s[64:65]
	s_waitcnt vmcnt(7)
	v_add_f32_e32 v14, v14, v164
	v_add_f32_e32 v10, v10, v165
	v_add_f32_e32 v6, v6, v166
	v_add_f32_e32 v2, v2, v167
	v_cvt_pk_bf16_f32 v228, v14, v10
	v_cvt_pk_bf16_f32 v229, v6, v2
	v_mul_f32_e32 v14, v14, v14
	v_fmac_f32_e32 v14, v10, v10
	v_fmac_f32_e32 v14, v6, v6
	v_fmac_f32_e32 v14, v2, v2
	s_add_u32 s62, s38, 0xb2000
	s_addc_u32 s63, s39, 0
	global_store_dwordx2 v128, v[228:229], s[62:63]
	s_waitcnt vmcnt(7)
; __device__ __forceinline__ unsigned cvt_pk_bf16(float lo, float hi) { unsigned r; asm("v_cvt_pk_bf16_f32 %0, %1, %2" : "=v"(r) : "v"(lo), "v"(hi)); return r; }
;     __device__ __forceinline__ void operator()(const f32x4 (&acc)[2][2][4][2], const Unit& u, int wr, int wc, int fr, int fq, LAS unsigned char* xs, int wid, int lane) const {
;     ...
;                         ss += (v0[0] * v0[0] + v0[1] * v0[1]) + (v0[2] * v0[2] + v0[3] * v0[3]) + (v1[0] * v1[0] + v1[1] * v1[1]) + (v1[2] * v1[2] + v1[3] * v1[3]);
;                         u32x4 w; w.x = cvt_pk_bf16(v0[0], v0[1]); w.y = cvt_pk_bf16(v0[2], v0[3]); w.z = cvt_pk_bf16(v1[0], v1[1]); w.w = cvt_pk_bf16(v1[2], v1[3]); *(u32x4*)(xb + o) = w;
;                     }
;                 }
;                 if (!LAST) { ss += __shfl_xor(ss, 16); ss += __shfl_xor(ss, 32);
;                     if (fq == 0) P[(ai * 128 + wr * 64 + m * 16 + fr) * 4 + wc] = ss; }
	v_add_f32_e32 v15, v15, v168
	v_add_f32_e32 v11, v11, v169
	v_add_f32_e32 v7, v7, v170
	v_add_f32_e32 v3, v3, v171
	v_cvt_pk_bf16_f32 v230, v15, v11
	v_cvt_pk_bf16_f32 v231, v7, v3
	v_mul_f32_e32 v15, v15, v15
	v_fmac_f32_e32 v15, v11, v11
	v_fmac_f32_e32 v15, v7, v7
	v_fmac_f32_e32 v15, v3, v3
	s_add_u32 s64, s38, 0xb3000
	s_addc_u32 s65, s39, 0
	global_store_dwordx2 v128, v[230:231], s[64:65]
	v_add_f32_dpp v124, v124, v124 quad_perm:[1,0,3,2] row_mask:0xf bank_mask:0xf
	v_add_f32_dpp v125, v125, v125 quad_perm:[1,0,3,2] row_mask:0xf bank_mask:0xf
	v_add_f32_dpp v126, v126, v126 quad_perm:[1,0,3,2] row_mask:0xf bank_mask:0xf
	v_add_f32_dpp v127, v127, v127 quad_perm:[1,0,3,2] row_mask:0xf bank_mask:0xf
	v_add_f32_dpp v124, v124, v124 quad_perm:[2,3,0,1] row_mask:0xf bank_mask:0xf
	v_add_f32_dpp v125, v125, v125 quad_perm:[2,3,0,1] row_mask:0xf bank_mask:0xf
	v_add_f32_dpp v126, v126, v126 quad_perm:[2,3,0,1] row_mask:0xf bank_mask:0xf
	v_add_f32_dpp v127, v127, v127 quad_perm:[2,3,0,1] row_mask:0xf bank_mask:0xf
	v_add_f32_dpp v124, v124, v124 row_half_mirror row_mask:0xf bank_mask:0xf
	v_add_f32_dpp v125, v125, v125 row_half_mirror row_mask:0xf bank_mask:0xf
	v_add_f32_dpp v126, v126, v126 row_half_mirror row_mask:0xf bank_mask:0xf
	v_add_f32_dpp v127, v127, v127 row_half_mirror row_mask:0xf bank_mask:0xf
	v_add_f32_dpp v124, v124, v124 row_mirror row_mask:0xf bank_mask:0xf
	v_add_f32_dpp v125, v125, v125 row_mirror row_mask:0xf bank_mask:0xf
	v_add_f32_dpp v126, v126, v126 row_mirror row_mask:0xf bank_mask:0xf
	v_add_f32_dpp v127, v127, v127 row_mirror row_mask:0xf bank_mask:0xf
	v_add_f32_dpp v108, v108, v108 quad_perm:[1,0,3,2] row_mask:0xf bank_mask:0xf
	v_add_f32_dpp v109, v109, v109 quad_perm:[1,0,3,2] row_mask:0xf bank_mask:0xf
	v_add_f32_dpp v110, v110, v110 quad_perm:[1,0,3,2] row_mask:0xf bank_mask:0xf
	v_add_f32_dpp v111, v111, v111 quad_perm:[1,0,3,2] row_mask:0xf bank_mask:0xf
	v_add_f32_dpp v108, v108, v108 quad_perm:[2,3,0,1] row_mask:0xf bank_mask:0xf
	v_add_f32_dpp v109, v109, v109 quad_perm:[2,3,0,1] row_mask:0xf bank_mask:0xf
	v_add_f32_dpp v110, v110, v110 quad_perm:[2,3,0,1] row_mask:0xf bank_mask:0xf
	v_add_f32_dpp v111, v111, v111 quad_perm:[2,3,0,1] row_mask:0xf bank_mask:0xf
	v_add_f32_dpp v108, v108, v108 row_half_mirror row_mask:0xf bank_mask:0xf
	v_add_f32_dpp v109, v109, v109 row_half_mirror row_mask:0xf bank_mask:0xf
	v_add_f32_dpp v110, v110, v110 row_half_mirror row_mask:0xf bank_mask:0xf
	v_add_f32_dpp v111, v111, v111 row_half_mirror row_mask:0xf bank_mask:0xf
	v_add_f32_dpp v108, v108, v108 row_mirror row_mask:0xf bank_mask:0xf
	v_add_f32_dpp v109, v109, v109 row_mirror row_mask:0xf bank_mask:0xf
	v_add_f32_dpp v110, v110, v110 row_mirror row_mask:0xf bank_mask:0xf
	v_add_f32_dpp v111, v111, v111 row_mirror row_mask:0xf bank_mask:0xf
	v_add_f32_dpp v92, v92, v92 quad_perm:[1,0,3,2] row_mask:0xf bank_mask:0xf
	v_add_f32_dpp v93, v93, v93 quad_perm:[1,0,3,2] row_mask:0xf bank_mask:0xf
	v_add_f32_dpp v94, v94, v94 quad_perm:[1,0,3,2] row_mask:0xf bank_mask:0xf
	v_add_f32_dpp v95, v95, v95 quad_perm:[1,0,3,2] row_mask:0xf bank_mask:0xf
	v_add_f32_dpp v92, v92, v92 quad_perm:[2,3,0,1] row_mask:0xf bank_mask:0xf
	v_add_f32_dpp v93, v93, v93 quad_perm:[2,3,0,1] row_mask:0xf bank_mask:0xf
	v_add_f32_dpp v94, v94, v94 quad_perm:[2,3,0,1] row_mask:0xf bank_mask:0xf
	v_add_f32_dpp v95, v95, v95 quad_perm:[2,3,0,1] row_mask:0xf bank_mask:0xf
	v_add_f32_dpp v92, v92, v92 row_half_mirror row_mask:0xf bank_mask:0xf
	v_add_f32_dpp v93, v93, v93 row_half_mirror row_mask:0xf bank_mask:0xf
	v_add_f32_dpp v94, v94, v94 row_half_mirror row_mask:0xf bank_mask:0xf
	v_add_f32_dpp v95, v95, v95 row_half_mirror row_mask:0xf bank_mask:0xf
	v_add_f32_dpp v92, v92, v92 row_mirror row_mask:0xf bank_mask:0xf
	v_add_f32_dpp v93, v93, v93 row_mirror row_mask:0xf bank_mask:0xf
	v_add_f32_dpp v94, v94, v94 row_mirror row_mask:0xf bank_mask:0xf
	v_add_f32_dpp v95, v95, v95 row_mirror row_mask:0xf bank_mask:0xf
	v_add_f32_dpp v76, v76, v76 quad_perm:[1,0,3,2] row_mask:0xf bank_mask:0xf
	v_add_f32_dpp v77, v77, v77 quad_perm:[1,0,3,2] row_mask:0xf bank_mask:0xf
	v_add_f32_dpp v78, v78, v78 quad_perm:[1,0,3,2] row_mask:0xf bank_mask:0xf
	v_add_f32_dpp v79, v79, v79 quad_perm:[1,0,3,2] row_mask:0xf bank_mask:0xf
	v_add_f32_dpp v76, v76, v76 quad_perm:[2,3,0,1] row_mask:0xf bank_mask:0xf
	v_add_f32_dpp v77, v77, v77 quad_perm:[2,3,0,1] row_mask:0xf bank_mask:0xf
	v_add_f32_dpp v78, v78, v78 quad_perm:[2,3,0,1] row_mask:0xf bank_mask:0xf
	v_add_f32_dpp v79, v79, v79 quad_perm:[2,3,0,1] row_mask:0xf bank_mask:0xf
	v_add_f32_dpp v76, v76, v76 row_half_mirror row_mask:0xf bank_mask:0xf
	v_add_f32_dpp v77, v77, v77 row_half_mirror row_mask:0xf bank_mask:0xf
	v_add_f32_dpp v78, v78, v78 row_half_mirror row_mask:0xf bank_mask:0xf
	v_add_f32_dpp v79, v79, v79 row_half_mirror row_mask:0xf bank_mask:0xf
	v_add_f32_dpp v76, v76, v76 row_mirror row_mask:0xf bank_mask:0xf
	v_add_f32_dpp v77, v77, v77 row_mirror row_mask:0xf bank_mask:0xf
	v_add_f32_dpp v78, v78, v78 row_mirror row_mask:0xf bank_mask:0xf
	v_add_f32_dpp v79, v79, v79 row_mirror row_mask:0xf bank_mask:0xf
	v_add_f32_dpp v60, v60, v60 quad_perm:[1,0,3,2] row_mask:0xf bank_mask:0xf
	v_add_f32_dpp v61, v61, v61 quad_perm:[1,0,3,2] row_mask:0xf bank_mask:0xf
	v_add_f32_dpp v62, v62, v62 quad_perm:[1,0,3,2] row_mask:0xf bank_mask:0xf
	v_add_f32_dpp v63, v63, v63 quad_perm:[1,0,3,2] row_mask:0xf bank_mask:0xf
	v_add_f32_dpp v60, v60, v60 quad_perm:[2,3,0,1] row_mask:0xf bank_mask:0xf
	v_add_f32_dpp v61, v61, v61 quad_perm:[2,3,0,1] row_mask:0xf bank_mask:0xf
; #define LAS __attribute__((address_space(3)))
; #define LDS_WAIT() asm volatile("s_waitcnt lgkmcnt(0)" ::: "memory")
;     __device__ __forceinline__ void operator()(const f32x4 (&acc)[2][2][4][2], const Unit& u, int wr, int wc, int fr, int fq, LAS unsigned char* xs, int wid, int lane) const {
;     ...
;                 if (!LAST) { ss += __shfl_xor(ss, 16); ss += __shfl_xor(ss, 32);
;                     if (fq == 0) P[(ai * 128 + wr * 64 + m * 16 + fr) * 4 + wc] = ss; }
;             }
;             if (SRCF32) __builtin_amdgcn_sched_barrier(0);
;         }
;         if (!LAST) {
;             LDS_WAIT();
;             __builtin_amdgcn_s_barrier();
;             const int tid = wid * 64 + lane;
;             if (tid < 256) { const f32x4 v = *(const LAS f32x4*)(P + tid * 4); rss[(size_t)(u.pm * 256 + tid) * 8 + u.pn] = (v[0] + v[1]) + (v[2] + v[3]); }
;             LDS_WAIT();
	v_add_f32_dpp v62, v62, v62 quad_perm:[2,3,0,1] row_mask:0xf bank_mask:0xf
	v_add_f32_dpp v63, v63, v63 quad_perm:[2,3,0,1] row_mask:0xf bank_mask:0xf
	v_add_f32_dpp v60, v60, v60 row_half_mirror row_mask:0xf bank_mask:0xf
	v_add_f32_dpp v61, v61, v61 row_half_mirror row_mask:0xf bank_mask:0xf
	v_add_f32_dpp v62, v62, v62 row_half_mirror row_mask:0xf bank_mask:0xf
	v_add_f32_dpp v63, v63, v63 row_half_mirror row_mask:0xf bank_mask:0xf
	v_add_f32_dpp v60, v60, v60 row_mirror row_mask:0xf bank_mask:0xf
	v_add_f32_dpp v61, v61, v61 row_mirror row_mask:0xf bank_mask:0xf
	v_add_f32_dpp v62, v62, v62 row_mirror row_mask:0xf bank_mask:0xf
	v_add_f32_dpp v63, v63, v63 row_mirror row_mask:0xf bank_mask:0xf
	v_add_f32_dpp v44, v44, v44 quad_perm:[1,0,3,2] row_mask:0xf bank_mask:0xf
	v_add_f32_dpp v45, v45, v45 quad_perm:[1,0,3,2] row_mask:0xf bank_mask:0xf
	v_add_f32_dpp v46, v46, v46 quad_perm:[1,0,3,2] row_mask:0xf bank_mask:0xf
	v_add_f32_dpp v47, v47, v47 quad_perm:[1,0,3,2] row_mask:0xf bank_mask:0xf
	v_add_f32_dpp v44, v44, v44 quad_perm:[2,3,0,1] row_mask:0xf bank_mask:0xf
	v_add_f32_dpp v45, v45, v45 quad_perm:[2,3,0,1] row_mask:0xf bank_mask:0xf
	v_add_f32_dpp v46, v46, v46 quad_perm:[2,3,0,1] row_mask:0xf bank_mask:0xf
	v_add_f32_dpp v47, v47, v47 quad_perm:[2,3,0,1] row_mask:0xf bank_mask:0xf
	v_add_f32_dpp v44, v44, v44 row_half_mirror row_mask:0xf bank_mask:0xf
	v_add_f32_dpp v45, v45, v45 row_half_mirror row_mask:0xf bank_mask:0xf
	v_add_f32_dpp v46, v46, v46 row_half_mirror row_mask:0xf bank_mask:0xf
	v_add_f32_dpp v47, v47, v47 row_half_mirror row_mask:0xf bank_mask:0xf
	v_add_f32_dpp v44, v44, v44 row_mirror row_mask:0xf bank_mask:0xf
	v_add_f32_dpp v45, v45, v45 row_mirror row_mask:0xf bank_mask:0xf
	v_add_f32_dpp v46, v46, v46 row_mirror row_mask:0xf bank_mask:0xf
	v_add_f32_dpp v47, v47, v47 row_mirror row_mask:0xf bank_mask:0xf
	v_add_f32_dpp v28, v28, v28 quad_perm:[1,0,3,2] row_mask:0xf bank_mask:0xf
	v_add_f32_dpp v29, v29, v29 quad_perm:[1,0,3,2] row_mask:0xf bank_mask:0xf
	v_add_f32_dpp v30, v30, v30 quad_perm:[1,0,3,2] row_mask:0xf bank_mask:0xf
	v_add_f32_dpp v31, v31, v31 quad_perm:[1,0,3,2] row_mask:0xf bank_mask:0xf
	v_add_f32_dpp v28, v28, v28 quad_perm:[2,3,0,1] row_mask:0xf bank_mask:0xf
	v_add_f32_dpp v29, v29, v29 quad_perm:[2,3,0,1] row_mask:0xf bank_mask:0xf
	v_add_f32_dpp v30, v30, v30 quad_perm:[2,3,0,1] row_mask:0xf bank_mask:0xf
	v_add_f32_dpp v31, v31, v31 quad_perm:[2,3,0,1] row_mask:0xf bank_mask:0xf
	v_add_f32_dpp v28, v28, v28 row_half_mirror row_mask:0xf bank_mask:0xf
	v_add_f32_dpp v29, v29, v29 row_half_mirror row_mask:0xf bank_mask:0xf
	v_add_f32_dpp v30, v30, v30 row_half_mirror row_mask:0xf bank_mask:0xf
	v_add_f32_dpp v31, v31, v31 row_half_mirror row_mask:0xf bank_mask:0xf
	v_add_f32_dpp v28, v28, v28 row_mirror row_mask:0xf bank_mask:0xf
	v_add_f32_dpp v29, v29, v29 row_mirror row_mask:0xf bank_mask:0xf
	v_add_f32_dpp v30, v30, v30 row_mirror row_mask:0xf bank_mask:0xf
	v_add_f32_dpp v31, v31, v31 row_mirror row_mask:0xf bank_mask:0xf
	v_add_f32_dpp v12, v12, v12 quad_perm:[1,0,3,2] row_mask:0xf bank_mask:0xf
	v_add_f32_dpp v13, v13, v13 quad_perm:[1,0,3,2] row_mask:0xf bank_mask:0xf
	v_add_f32_dpp v14, v14, v14 quad_perm:[1,0,3,2] row_mask:0xf bank_mask:0xf
	v_add_f32_dpp v15, v15, v15 quad_perm:[1,0,3,2] row_mask:0xf bank_mask:0xf
	v_add_f32_dpp v12, v12, v12 quad_perm:[2,3,0,1] row_mask:0xf bank_mask:0xf
	v_add_f32_dpp v13, v13, v13 quad_perm:[2,3,0,1] row_mask:0xf bank_mask:0xf
	v_add_f32_dpp v14, v14, v14 quad_perm:[2,3,0,1] row_mask:0xf bank_mask:0xf
	v_add_f32_dpp v15, v15, v15 quad_perm:[2,3,0,1] row_mask:0xf bank_mask:0xf
	v_add_f32_dpp v12, v12, v12 row_half_mirror row_mask:0xf bank_mask:0xf
	v_add_f32_dpp v13, v13, v13 row_half_mirror row_mask:0xf bank_mask:0xf
	v_add_f32_dpp v14, v14, v14 row_half_mirror row_mask:0xf bank_mask:0xf
	v_add_f32_dpp v15, v15, v15 row_half_mirror row_mask:0xf bank_mask:0xf
	v_add_f32_dpp v12, v12, v12 row_mirror row_mask:0xf bank_mask:0xf
	v_add_f32_dpp v13, v13, v13 row_mirror row_mask:0xf bank_mask:0xf
	v_add_f32_dpp v14, v14, v14 row_mirror row_mask:0xf bank_mask:0xf
	v_add_f32_dpp v15, v15, v15 row_mirror row_mask:0xf bank_mask:0xf
	s_mov_b32 exec_lo, 0x10001
	s_mov_b32 exec_hi, 0x10001
	ds_write_b32 v137, v124 offset:0
	ds_write_b32 v137, v125 offset:16
	ds_write_b32 v137, v126 offset:32
	ds_write_b32 v137, v127 offset:48
	ds_write_b32 v137, v108 offset:256
	ds_write_b32 v137, v109 offset:272
	ds_write_b32 v137, v110 offset:288
	ds_write_b32 v137, v111 offset:304
	ds_write_b32 v137, v92 offset:512
	ds_write_b32 v137, v93 offset:528
	ds_write_b32 v137, v94 offset:544
	ds_write_b32 v137, v95 offset:560
	ds_write_b32 v137, v76 offset:768
	ds_write_b32 v137, v77 offset:784
	ds_write_b32 v137, v78 offset:800
	ds_write_b32 v137, v79 offset:816
	ds_write_b32 v137, v60 offset:2048
	ds_write_b32 v137, v61 offset:2064
	ds_write_b32 v137, v62 offset:2080
	ds_write_b32 v137, v63 offset:2096
	ds_write_b32 v137, v44 offset:2304
	ds_write_b32 v137, v45 offset:2320
	ds_write_b32 v137, v46 offset:2336
	ds_write_b32 v137, v47 offset:2352
	ds_write_b32 v137, v28 offset:2560
	ds_write_b32 v137, v29 offset:2576
	ds_write_b32 v137, v30 offset:2592
	ds_write_b32 v137, v31 offset:2608
	ds_write_b32 v137, v12 offset:2816
	ds_write_b32 v137, v13 offset:2832
	ds_write_b32 v137, v14 offset:2848
	ds_write_b32 v137, v15 offset:2864
	s_mov_b64 exec, -1
	s_waitcnt lgkmcnt(0)
	s_barrier
	v_cmp_gt_u32_e32 vcc, 0x100, v254
	s_and_saveexec_b64 s[62:63], vcc
	v_lshlrev_b32_e32 v134, 4, v254
	v_add_u32_e32 v134, 0x20000, v134
	ds_read_b128 v[224:227], v134
	v_add_u32_e32 v136, s41, v254
	v_lshlrev_b32_e32 v136, 5, v136
	s_lshl_b32 s18, s46, 2
	v_add_u32_e32 v136, s18, v136
	s_waitcnt lgkmcnt(0)
	v_add_f32_e32 v224, v224, v225
	v_add_f32_e32 v226, v226, v227
	v_add_f32_e32 v224, v224, v226
	global_store_dword v136, v224, s[30:31]
	s_or_b64 exec, exec, s[62:63]
	s_andn2_b64 vcc, exec, s[10:11]
	s_mov_b64 s[10:11], -1
	s_cbranch_vccnz .LBB0_611
	s_andn2_b64 vcc, exec, s[36:37]
	s_cbranch_vccnz .LBB0_610
	s_barrier
	s_branch .LBB0_610

; #define LAS __attribute__((address_space(3)))
;     __device__ __forceinline__ void operator()(const f32x4 (&acc)[2][2][4][2], const Unit& u, int wr, int wc, int fr, int fq, LAS unsigned char* xs, int wid, int lane) const {
;         const int row0 = u.pm * 256 + wr * 64, col0 = u.pn * 256 + wc * 32 + 8 * fq;
;         const float* xo = (row0 < TP) ? xo_p : xo_s - (size_t)TP * D;
;         LAS float* P = (LAS float*)xs;
;         u32x4 raw[2][4][2];
;         if (!SRCF32) {
; #pragma unroll
;             for (int ai = 0; ai < 2; ++ai)
; #pragma unroll
;                 for (int m = 0; m < 4; ++m)
; #pragma unroll
;                     for (int bj = 0; bj < 2; ++bj) raw[ai][m][bj] = *(const u32x4*)(xb + (size_t)(row0 + ai * 128 + m * 16 + fr) * D + col0 + bj * 128);
;         }
; #pragma unroll
;         for (int ai = 0; ai < 2; ++ai) {
;             f32x4 xf[4][2][2];
;             if (SRCF32) {
; #pragma unroll
;                 for (int m = 0; m < 4; ++m)
; #pragma unroll
;                     for (int bj = 0; bj < 2; ++bj) { const size_t o = (size_t)(row0 + ai * 128 + m * 16 + fr) * D + col0 + bj * 128; xf[m][bj][0] = *(const f32x4*)(xo + o); xf[m][bj][1] = *(const f32x4*)(xo + o + 4); }
;             }
; #pragma unroll
;             for (int m = 0; m < 4; ++m) {
;                 const size_t row = (size_t)(row0 + ai * 128 + m * 16 + fr);
;                 float ss = 0.f;
; #pragma unroll
;                 for (int bj = 0; bj < 2; ++bj) {
;                     const size_t o = row * D + col0 + bj * 128;
;                     f32x4 x0, x1;
;                     if (SRCF32) { x0 = xf[m][bj][0]; x1 = xf[m][bj][1]; }
;                     else { const u32x4 r = raw[ai][m][bj]; x0 = (f32x4){bf_lo(r.x), bf_hi(r.x), bf_lo(r.y), bf_hi(r.y)}; x1 = (f32x4){bf_lo(r.z), bf_hi(r.z), bf_lo(r.w), bf_hi(r.w)}; }
;                     const f32x4 v0 = x0 + acc[ai][bj][m][0], v1 = x1 + acc[ai][bj][m][1];
;                     if (LAST) { *(f32x4*)(out + o) = v0; *(f32x4*)(out + o + 4) = v1; }
.LBB0_1628:
	v_readfirstlane_b32 s52, v254
	s_nop 1
	s_lshr_b32 s52, s52, 6
	s_lshr_b32 s53, s52, 2
	s_and_b32 s65, s52, 3
	s_lshl_b32 s64, s26, 8
	s_lshl_b32 s53, s53, 6
	s_add_i32 s54, s64, s53
	s_lshl_b32 s55, s46, 8
	s_lshl_b32 s52, s65, 6
	s_add_i32 s55, s55, s52
	s_lshl_b32 s54, s54, 11
	s_add_i32 s54, s54, s55
	s_lshl_b32 s55, s54, 1
	s_add_u32 s56, s16, s55
	s_addc_u32 s57, s17, 0
	s_lshl_b32 s55, s54, 2
	s_add_u32 s58, s4, s55
	s_addc_u32 s59, s5, 0
	v_and_b32_e32 v246, 15, v254
	v_bfe_u32 v247, v254, 4, 2
	v_lshlrev_b32_e32 v245, 13, v247
	v_lshl_add_u32 v245, v246, 2, v245
	v_lshlrev_b32_e32 v244, 1, v245
	v_lshlrev_b32_e32 v245, 2, v245
	s_add_u32 s60, s56, 0x0
	s_addc_u32 s61, s57, 0
	global_load_dwordx2 v[128:129], v244, s[60:61]
	s_add_u32 s62, s56, 0x1000
	s_addc_u32 s63, s57, 0
	global_load_dwordx2 v[130:131], v244, s[62:63]
	s_add_u32 s60, s56, 0x2000
	s_addc_u32 s61, s57, 0
	global_load_dwordx2 v[132:133], v244, s[60:61]
	s_add_u32 s62, s56, 0x3000
	s_addc_u32 s63, s57, 0
	global_load_dwordx2 v[134:135], v244, s[62:63]
	s_add_u32 s60, s56, 0x10000
	s_addc_u32 s61, s57, 0
	global_load_dwordx2 v[136:137], v244, s[60:61]
	s_add_u32 s62, s56, 0x11000
	s_addc_u32 s63, s57, 0
	global_load_dwordx2 v[138:139], v244, s[62:63]
	s_add_u32 s60, s56, 0x12000
	s_addc_u32 s61, s57, 0
	global_load_dwordx2 v[140:141], v244, s[60:61]
	s_add_u32 s62, s56, 0x13000
	s_addc_u32 s63, s57, 0
	global_load_dwordx2 v[142:143], v244, s[62:63]
	s_add_u32 s60, s56, 0x20000
	s_addc_u32 s61, s57, 0
	global_load_dwordx2 v[144:145], v244, s[60:61]
	s_add_u32 s62, s56, 0x21000
	s_addc_u32 s63, s57, 0
	global_load_dwordx2 v[146:147], v244, s[62:63]
	s_add_u32 s60, s56, 0x22000
	s_addc_u32 s61, s57, 0
	global_load_dwordx2 v[148:149], v244, s[60:61]
	s_add_u32 s62, s56, 0x23000
	s_addc_u32 s63, s57, 0
	global_load_dwordx2 v[150:151], v244, s[62:63]
	s_add_u32 s60, s56, 0x30000
	s_addc_u32 s61, s57, 0
	global_load_dwordx2 v[152:153], v244, s[60:61]
	s_add_u32 s62, s56, 0x31000
	s_addc_u32 s63, s57, 0
	global_load_dwordx2 v[154:155], v244, s[62:63]
	s_add_u32 s60, s56, 0x32000
	s_addc_u32 s61, s57, 0
	global_load_dwordx2 v[156:157], v244, s[60:61]
	s_add_u32 s62, s56, 0x33000
	s_addc_u32 s63, s57, 0
	global_load_dwordx2 v[158:159], v244, s[62:63]
	s_add_u32 s60, s56, 0x80000
	s_addc_u32 s61, s57, 0
	global_load_dwordx2 v[160:161], v244, s[60:61]
	s_add_u32 s62, s56, 0x81000
	s_addc_u32 s63, s57, 0
	global_load_dwordx2 v[162:163], v244, s[62:63]
	s_add_u32 s60, s56, 0x82000
	s_addc_u32 s61, s57, 0
	global_load_dwordx2 v[200:201], v244, s[60:61]
	s_add_u32 s62, s56, 0x83000
	s_addc_u32 s63, s57, 0
	global_load_dwordx2 v[202:203], v244, s[62:63]
	s_add_u32 s60, s56, 0x90000
	s_addc_u32 s61, s57, 0
	global_load_dwordx2 v[204:205], v244, s[60:61]
	s_add_u32 s62, s56, 0x91000
	s_addc_u32 s63, s57, 0
	global_load_dwordx2 v[206:207], v244, s[62:63]
	s_add_u32 s60, s56, 0x92000
	s_addc_u32 s61, s57, 0
	global_load_dwordx2 v[208:209], v244, s[60:61]
	s_add_u32 s62, s56, 0x93000
	s_addc_u32 s63, s57, 0
	global_load_dwordx2 v[210:211], v244, s[62:63]
	s_add_u32 s60, s56, 0xa0000
	s_addc_u32 s61, s57, 0
	global_load_dwordx2 v[212:213], v244, s[60:61]
	s_add_u32 s62, s56, 0xa1000
	s_addc_u32 s63, s57, 0
	global_load_dwordx2 v[214:215], v244, s[62:63]
	s_add_u32 s60, s56, 0xa2000
	s_addc_u32 s61, s57, 0
	global_load_dwordx2 v[216:217], v244, s[60:61]
	s_add_u32 s62, s56, 0xa3000
	s_addc_u32 s63, s57, 0
	global_load_dwordx2 v[218:219], v244, s[62:63]
	s_add_u32 s60, s56, 0xb0000
	s_addc_u32 s61, s57, 0
	global_load_dwordx2 v[220:221], v244, s[60:61]
	s_add_u32 s62, s56, 0xb1000
	s_addc_u32 s63, s57, 0
	global_load_dwordx2 v[222:223], v244, s[62:63]
	s_add_u32 s60, s56, 0xb2000
	s_addc_u32 s61, s57, 0
	global_load_dwordx2 v[224:225], v244, s[60:61]
	s_add_u32 s62, s56, 0xb3000
	s_addc_u32 s63, s57, 0
	global_load_dwordx2 v[226:227], v244, s[62:63]
	s_waitcnt vmcnt(31)
	v_lshlrev_b32_e32 v248, 16, v128
	v_and_b32_e32 v249, 0xffff0000, v128
	v_add_f32_e32 v228, v124, v248
	v_add_f32_e32 v229, v120, v249
	v_lshlrev_b32_e32 v248, 16, v129
	v_and_b32_e32 v249, 0xffff0000, v129
	v_add_f32_e32 v230, v116, v248
	v_add_f32_e32 v231, v112, v249
	s_add_u32 s60, s58, 0x0
	s_addc_u32 s61, s59, 0
	global_store_dwordx4 v245, v[228:231], s[60:61]
	s_waitcnt vmcnt(31)
	v_lshlrev_b32_e32 v248, 16, v130
	v_and_b32_e32 v249, 0xffff0000, v130
	v_add_f32_e32 v232, v125, v248
	v_add_f32_e32 v233, v121, v249
	v_lshlrev_b32_e32 v248, 16, v131
	v_and_b32_e32 v249, 0xffff0000, v131
	v_add_f32_e32 v234, v117, v248
	v_add_f32_e32 v235, v113, v249
	s_add_u32 s62, s58, 0x2000
	s_addc_u32 s63, s59, 0
	global_store_dwordx4 v245, v[232:235], s[62:63]
	s_waitcnt vmcnt(31)
	v_lshlrev_b32_e32 v248, 16, v132
	v_and_b32_e32 v249, 0xffff0000, v132
	v_add_f32_e32 v236, v126, v248
	v_add_f32_e32 v237, v122, v249
	v_lshlrev_b32_e32 v248, 16, v133
	v_and_b32_e32 v249, 0xffff0000, v133
	v_add_f32_e32 v238, v118, v248
	v_add_f32_e32 v239, v114, v249
	s_add_u32 s60, s58, 0x4000
	s_addc_u32 s61, s59, 0
	global_store_dwordx4 v245, v[236:239], s[60:61]
	s_waitcnt vmcnt(31)
	v_lshlrev_b32_e32 v248, 16, v134
	v_and_b32_e32 v249, 0xffff0000, v134
	v_add_f32_e32 v240, v127, v248
	v_add_f32_e32 v241, v123, v249
	v_lshlrev_b32_e32 v248, 16, v135
	v_and_b32_e32 v249, 0xffff0000, v135
	v_add_f32_e32 v242, v119, v248
	v_add_f32_e32 v243, v115, v249
	s_add_u32 s62, s58, 0x6000
	s_addc_u32 s63, s59, 0
	global_store_dwordx4 v245, v[240:243], s[62:63]
	s_waitcnt vmcnt(31)
;     __device__ __forceinline__ void operator()(const f32x4 (&acc)[2][2][4][2], const Unit& u, int wr, int wc, int fr, int fq, LAS unsigned char* xs, int wid, int lane) const {
;     ...
;                 const size_t row = (size_t)(row0 + ai * 128 + m * 16 + fr);
;                 float ss = 0.f;
; #pragma unroll
;                 for (int bj = 0; bj < 2; ++bj) {
;                     const size_t o = row * D + col0 + bj * 128;
;                     f32x4 x0, x1;
;                     if (SRCF32) { x0 = xf[m][bj][0]; x1 = xf[m][bj][1]; }
;                     else { const u32x4 r = raw[ai][m][bj]; x0 = (f32x4){bf_lo(r.x), bf_hi(r.x), bf_lo(r.y), bf_hi(r.y)}; x1 = (f32x4){bf_lo(r.z), bf_hi(r.z), bf_lo(r.w), bf_hi(r.w)}; }
;                     const f32x4 v0 = x0 + acc[ai][bj][m][0], v1 = x1 + acc[ai][bj][m][1];
;                     if (LAST) { *(f32x4*)(out + o) = v0; *(f32x4*)(out + o + 4) = v1; }
	v_lshlrev_b32_e32 v248, 16, v136
	v_and_b32_e32 v249, 0xffff0000, v136
	v_add_f32_e32 v228, v108, v248
	v_add_f32_e32 v229, v104, v249
	v_lshlrev_b32_e32 v248, 16, v137
	v_and_b32_e32 v249, 0xffff0000, v137
	v_add_f32_e32 v230, v100, v248
	v_add_f32_e32 v231, v92, v249
	s_add_u32 s60, s58, 0x20000
	s_addc_u32 s61, s59, 0
	global_store_dwordx4 v245, v[228:231], s[60:61]
	s_waitcnt vmcnt(31)
	v_lshlrev_b32_e32 v248, 16, v138
	v_and_b32_e32 v249, 0xffff0000, v138
	v_add_f32_e32 v232, v109, v248
	v_add_f32_e32 v233, v105, v249
	v_lshlrev_b32_e32 v248, 16, v139
	v_and_b32_e32 v249, 0xffff0000, v139
	v_add_f32_e32 v234, v101, v248
	v_add_f32_e32 v235, v93, v249
	s_add_u32 s62, s58, 0x22000
	s_addc_u32 s63, s59, 0
	global_store_dwordx4 v245, v[232:235], s[62:63]
	s_waitcnt vmcnt(31)
	v_lshlrev_b32_e32 v248, 16, v140
	v_and_b32_e32 v249, 0xffff0000, v140
	v_add_f32_e32 v236, v110, v248
	v_add_f32_e32 v237, v106, v249
	v_lshlrev_b32_e32 v248, 16, v141
	v_and_b32_e32 v249, 0xffff0000, v141
	v_add_f32_e32 v238, v102, v248
	v_add_f32_e32 v239, v94, v249
	s_add_u32 s60, s58, 0x24000
	s_addc_u32 s61, s59, 0
	global_store_dwordx4 v245, v[236:239], s[60:61]
	s_waitcnt vmcnt(31)
	v_lshlrev_b32_e32 v248, 16, v142
	v_and_b32_e32 v249, 0xffff0000, v142
	v_add_f32_e32 v240, v111, v248
	v_add_f32_e32 v241, v107, v249
	v_lshlrev_b32_e32 v248, 16, v143
	v_and_b32_e32 v249, 0xffff0000, v143
	v_add_f32_e32 v242, v103, v248
	v_add_f32_e32 v243, v95, v249
	s_add_u32 s62, s58, 0x26000
	s_addc_u32 s63, s59, 0
	global_store_dwordx4 v245, v[240:243], s[62:63]
	s_waitcnt vmcnt(31)
	v_lshlrev_b32_e32 v248, 16, v144
	v_and_b32_e32 v249, 0xffff0000, v144
	v_add_f32_e32 v228, v96, v248
	v_add_f32_e32 v229, v88, v249
	v_lshlrev_b32_e32 v248, 16, v145
	v_and_b32_e32 v249, 0xffff0000, v145
	v_add_f32_e32 v230, v84, v248
	v_add_f32_e32 v231, v76, v249
	s_add_u32 s60, s58, 0x40000
	s_addc_u32 s61, s59, 0
	global_store_dwordx4 v245, v[228:231], s[60:61]
	s_waitcnt vmcnt(31)
	v_lshlrev_b32_e32 v248, 16, v146
	v_and_b32_e32 v249, 0xffff0000, v146
	v_add_f32_e32 v232, v97, v248
	v_add_f32_e32 v233, v89, v249
	v_lshlrev_b32_e32 v248, 16, v147
	v_and_b32_e32 v249, 0xffff0000, v147
	v_add_f32_e32 v234, v85, v248
	v_add_f32_e32 v235, v77, v249
	s_add_u32 s62, s58, 0x42000
	s_addc_u32 s63, s59, 0
	global_store_dwordx4 v245, v[232:235], s[62:63]
	s_waitcnt vmcnt(31)
	v_lshlrev_b32_e32 v248, 16, v148
	v_and_b32_e32 v249, 0xffff0000, v148
	v_add_f32_e32 v236, v98, v248
	v_add_f32_e32 v237, v90, v249
	v_lshlrev_b32_e32 v248, 16, v149
	v_and_b32_e32 v249, 0xffff0000, v149
	v_add_f32_e32 v238, v86, v248
	v_add_f32_e32 v239, v78, v249
	s_add_u32 s60, s58, 0x44000
	s_addc_u32 s61, s59, 0
	global_store_dwordx4 v245, v[236:239], s[60:61]
	s_waitcnt vmcnt(31)
	v_lshlrev_b32_e32 v248, 16, v150
	v_and_b32_e32 v249, 0xffff0000, v150
	v_add_f32_e32 v240, v99, v248
	v_add_f32_e32 v241, v91, v249
	v_lshlrev_b32_e32 v248, 16, v151
	v_and_b32_e32 v249, 0xffff0000, v151
	v_add_f32_e32 v242, v87, v248
	v_add_f32_e32 v243, v79, v249
	s_add_u32 s62, s58, 0x46000
	s_addc_u32 s63, s59, 0
	global_store_dwordx4 v245, v[240:243], s[62:63]
	s_waitcnt vmcnt(31)
	v_lshlrev_b32_e32 v248, 16, v152
	v_and_b32_e32 v249, 0xffff0000, v152
	v_add_f32_e32 v228, v80, v248
	v_add_f32_e32 v229, v72, v249
	v_lshlrev_b32_e32 v248, 16, v153
	v_and_b32_e32 v249, 0xffff0000, v153
	v_add_f32_e32 v230, v68, v248
	v_add_f32_e32 v231, v64, v249
	s_add_u32 s60, s58, 0x60000
	s_addc_u32 s61, s59, 0
	global_store_dwordx4 v245, v[228:231], s[60:61]
	s_waitcnt vmcnt(31)
	v_lshlrev_b32_e32 v248, 16, v154
	v_and_b32_e32 v249, 0xffff0000, v154
	v_add_f32_e32 v232, v81, v248
	v_add_f32_e32 v233, v73, v249
	v_lshlrev_b32_e32 v248, 16, v155
	v_and_b32_e32 v249, 0xffff0000, v155
	v_add_f32_e32 v234, v69, v248
	v_add_f32_e32 v235, v65, v249
	s_add_u32 s62, s58, 0x62000
	s_addc_u32 s63, s59, 0
	global_store_dwordx4 v245, v[232:235], s[62:63]
	s_waitcnt vmcnt(31)
	v_lshlrev_b32_e32 v248, 16, v156
	v_and_b32_e32 v249, 0xffff0000, v156
	v_add_f32_e32 v236, v82, v248
	v_add_f32_e32 v237, v74, v249
	v_lshlrev_b32_e32 v248, 16, v157
	v_and_b32_e32 v249, 0xffff0000, v157
	v_add_f32_e32 v238, v70, v248
	v_add_f32_e32 v239, v66, v249
	s_add_u32 s60, s58, 0x64000
	s_addc_u32 s61, s59, 0
	global_store_dwordx4 v245, v[236:239], s[60:61]
	s_waitcnt vmcnt(31)
	v_lshlrev_b32_e32 v248, 16, v158
	v_and_b32_e32 v249, 0xffff0000, v158
	v_add_f32_e32 v240, v83, v248
	v_add_f32_e32 v241, v75, v249
	v_lshlrev_b32_e32 v248, 16, v159
	v_and_b32_e32 v249, 0xffff0000, v159
	v_add_f32_e32 v242, v71, v248
	v_add_f32_e32 v243, v67, v249
	s_add_u32 s62, s58, 0x66000
	s_addc_u32 s63, s59, 0
	global_store_dwordx4 v245, v[240:243], s[62:63]
	s_waitcnt vmcnt(31)
	v_lshlrev_b32_e32 v248, 16, v160
	v_and_b32_e32 v249, 0xffff0000, v160
	v_add_f32_e32 v228, v60, v248
	v_add_f32_e32 v229, v56, v249
	v_lshlrev_b32_e32 v248, 16, v161
	v_and_b32_e32 v249, 0xffff0000, v161
	v_add_f32_e32 v230, v52, v248
	v_add_f32_e32 v231, v44, v249
	s_add_u32 s60, s58, 0x100000
	s_addc_u32 s61, s59, 0
	global_store_dwordx4 v245, v[228:231], s[60:61]
	s_waitcnt vmcnt(31)
	v_lshlrev_b32_e32 v248, 16, v162
	v_and_b32_e32 v249, 0xffff0000, v162
	v_add_f32_e32 v232, v61, v248
	v_add_f32_e32 v233, v57, v249
	v_lshlrev_b32_e32 v248, 16, v163
	v_and_b32_e32 v249, 0xffff0000, v163
	v_add_f32_e32 v234, v53, v248
	v_add_f32_e32 v235, v45, v249
	s_add_u32 s62, s58, 0x102000
	s_addc_u32 s63, s59, 0
	global_store_dwordx4 v245, v[232:235], s[62:63]
	s_waitcnt vmcnt(31)
; #define PG8_BAR __builtin_amdgcn_s_barrier()
; template <class Epi, class Sched>
; __device__ __forceinline__ void gemm_phase(LAS unsigned char* lds, const int K, const int lda, const int ldb, const Sched& S, const Epi& E) {
;     ...
;         if (!has_next) break;
; #pragma unroll
;         for (int a = 0; a < 2; ++a)
; #pragma unroll
;             for (int b = 0; b < 2; ++b)
; #pragma unroll
;                 for (int m = 0; m < 4; ++m)
; #pragma unroll
;                     for (int n = 0; n < 2; ++n) acc[a][b][m][n] = (f32x4){0.f, 0.f, 0.f, 0.f};
;         cur = nxt; cA = nA; cB = nB; ++ui;
;         if (wr == 1) PG8_BAR;
;     __device__ __forceinline__ void operator()(const f32x4 (&acc)[2][2][4][2], const Unit& u, int wr, int wc, int fr, int fq, LAS unsigned char* xs, int wid, int lane) const {
;     ...
;                 const size_t row = (size_t)(row0 + ai * 128 + m * 16 + fr);
;                 float ss = 0.f;
; #pragma unroll
;                 for (int bj = 0; bj < 2; ++bj) {
;                     const size_t o = row * D + col0 + bj * 128;
;                     f32x4 x0, x1;
;                     if (SRCF32) { x0 = xf[m][bj][0]; x1 = xf[m][bj][1]; }
;                     else { const u32x4 r = raw[ai][m][bj]; x0 = (f32x4){bf_lo(r.x), bf_hi(r.x), bf_lo(r.y), bf_hi(r.y)}; x1 = (f32x4){bf_lo(r.z), bf_hi(r.z), bf_lo(r.w), bf_hi(r.w)}; }
;                     const f32x4 v0 = x0 + acc[ai][bj][m][0], v1 = x1 + acc[ai][bj][m][1];
;                     if (LAST) { *(f32x4*)(out + o) = v0; *(f32x4*)(out + o + 4) = v1; }
	v_lshlrev_b32_e32 v248, 16, v200
	v_and_b32_e32 v249, 0xffff0000, v200
	v_add_f32_e32 v236, v62, v248
	v_add_f32_e32 v237, v58, v249
	v_lshlrev_b32_e32 v248, 16, v201
	v_and_b32_e32 v249, 0xffff0000, v201
	v_add_f32_e32 v238, v54, v248
	v_add_f32_e32 v239, v46, v249
	s_add_u32 s60, s58, 0x104000
	s_addc_u32 s61, s59, 0
	global_store_dwordx4 v245, v[236:239], s[60:61]
	s_waitcnt vmcnt(31)
	v_lshlrev_b32_e32 v248, 16, v202
	v_and_b32_e32 v249, 0xffff0000, v202
	v_add_f32_e32 v240, v63, v248
	v_add_f32_e32 v241, v59, v249
	v_lshlrev_b32_e32 v248, 16, v203
	v_and_b32_e32 v249, 0xffff0000, v203
	v_add_f32_e32 v242, v55, v248
	v_add_f32_e32 v243, v47, v249
	s_add_u32 s62, s58, 0x106000
	s_addc_u32 s63, s59, 0
	global_store_dwordx4 v245, v[240:243], s[62:63]
	s_waitcnt vmcnt(31)
	v_lshlrev_b32_e32 v248, 16, v204
	v_and_b32_e32 v249, 0xffff0000, v204
	v_add_f32_e32 v228, v48, v248
	v_add_f32_e32 v229, v40, v249
	v_lshlrev_b32_e32 v248, 16, v205
	v_and_b32_e32 v249, 0xffff0000, v205
	v_add_f32_e32 v230, v36, v248
	v_add_f32_e32 v231, v28, v249
	s_add_u32 s60, s58, 0x120000
	s_addc_u32 s61, s59, 0
	global_store_dwordx4 v245, v[228:231], s[60:61]
	s_waitcnt vmcnt(31)
	v_lshlrev_b32_e32 v248, 16, v206
	v_and_b32_e32 v249, 0xffff0000, v206
	v_add_f32_e32 v232, v49, v248
	v_add_f32_e32 v233, v41, v249
	v_lshlrev_b32_e32 v248, 16, v207
	v_and_b32_e32 v249, 0xffff0000, v207
	v_add_f32_e32 v234, v37, v248
	v_add_f32_e32 v235, v29, v249
	s_add_u32 s62, s58, 0x122000
	s_addc_u32 s63, s59, 0
	global_store_dwordx4 v245, v[232:235], s[62:63]
	s_waitcnt vmcnt(31)
	v_lshlrev_b32_e32 v248, 16, v208
	v_and_b32_e32 v249, 0xffff0000, v208
	v_add_f32_e32 v236, v50, v248
	v_add_f32_e32 v237, v42, v249
	v_lshlrev_b32_e32 v248, 16, v209
	v_and_b32_e32 v249, 0xffff0000, v209
	v_add_f32_e32 v238, v38, v248
	v_add_f32_e32 v239, v30, v249
	s_add_u32 s60, s58, 0x124000
	s_addc_u32 s61, s59, 0
	global_store_dwordx4 v245, v[236:239], s[60:61]
	s_waitcnt vmcnt(31)
	v_lshlrev_b32_e32 v248, 16, v210
	v_and_b32_e32 v249, 0xffff0000, v210
	v_add_f32_e32 v240, v51, v248
	v_add_f32_e32 v241, v43, v249
	v_lshlrev_b32_e32 v248, 16, v211
	v_and_b32_e32 v249, 0xffff0000, v211
	v_add_f32_e32 v242, v39, v248
	v_add_f32_e32 v243, v31, v249
	s_add_u32 s62, s58, 0x126000
	s_addc_u32 s63, s59, 0
	global_store_dwordx4 v245, v[240:243], s[62:63]
	s_waitcnt vmcnt(31)
	v_lshlrev_b32_e32 v248, 16, v212
	v_and_b32_e32 v249, 0xffff0000, v212
	v_add_f32_e32 v228, v32, v248
	v_add_f32_e32 v229, v24, v249
	v_lshlrev_b32_e32 v248, 16, v213
	v_and_b32_e32 v249, 0xffff0000, v213
	v_add_f32_e32 v230, v20, v248
	v_add_f32_e32 v231, v12, v249
	s_add_u32 s60, s58, 0x140000
	s_addc_u32 s61, s59, 0
	global_store_dwordx4 v245, v[228:231], s[60:61]
	s_waitcnt vmcnt(31)
	v_lshlrev_b32_e32 v248, 16, v214
	v_and_b32_e32 v249, 0xffff0000, v214
	v_add_f32_e32 v232, v33, v248
	v_add_f32_e32 v233, v25, v249
	v_lshlrev_b32_e32 v248, 16, v215
	v_and_b32_e32 v249, 0xffff0000, v215
	v_add_f32_e32 v234, v21, v248
	v_add_f32_e32 v235, v13, v249
	s_add_u32 s62, s58, 0x142000
	s_addc_u32 s63, s59, 0
	global_store_dwordx4 v245, v[232:235], s[62:63]
	s_waitcnt vmcnt(31)
	v_lshlrev_b32_e32 v248, 16, v216
	v_and_b32_e32 v249, 0xffff0000, v216
	v_add_f32_e32 v236, v34, v248
	v_add_f32_e32 v237, v26, v249
	v_lshlrev_b32_e32 v248, 16, v217
	v_and_b32_e32 v249, 0xffff0000, v217
	v_add_f32_e32 v238, v22, v248
	v_add_f32_e32 v239, v14, v249
	s_add_u32 s60, s58, 0x144000
	s_addc_u32 s61, s59, 0
	global_store_dwordx4 v245, v[236:239], s[60:61]
	s_waitcnt vmcnt(31)
	v_lshlrev_b32_e32 v248, 16, v218
	v_and_b32_e32 v249, 0xffff0000, v218
	v_add_f32_e32 v240, v35, v248
	v_add_f32_e32 v241, v27, v249
	v_lshlrev_b32_e32 v248, 16, v219
	v_and_b32_e32 v249, 0xffff0000, v219
	v_add_f32_e32 v242, v23, v248
	v_add_f32_e32 v243, v15, v249
	s_add_u32 s62, s58, 0x146000
	s_addc_u32 s63, s59, 0
	global_store_dwordx4 v245, v[240:243], s[62:63]
	s_waitcnt vmcnt(31)
	v_lshlrev_b32_e32 v248, 16, v220
	v_and_b32_e32 v249, 0xffff0000, v220
	v_add_f32_e32 v228, v16, v248
	v_add_f32_e32 v229, v8, v249
	v_lshlrev_b32_e32 v248, 16, v221
	v_and_b32_e32 v249, 0xffff0000, v221
	v_add_f32_e32 v230, v4, v248
	v_add_f32_e32 v231, v0, v249
	s_add_u32 s60, s58, 0x160000
	s_addc_u32 s61, s59, 0
	global_store_dwordx4 v245, v[228:231], s[60:61]
	s_waitcnt vmcnt(31)
	v_lshlrev_b32_e32 v248, 16, v222
	v_and_b32_e32 v249, 0xffff0000, v222
	v_add_f32_e32 v232, v17, v248
	v_add_f32_e32 v233, v9, v249
	v_lshlrev_b32_e32 v248, 16, v223
	v_and_b32_e32 v249, 0xffff0000, v223
	v_add_f32_e32 v234, v5, v248
	v_add_f32_e32 v235, v1, v249
	s_add_u32 s62, s58, 0x162000
	s_addc_u32 s63, s59, 0
	global_store_dwordx4 v245, v[232:235], s[62:63]
	s_waitcnt vmcnt(31)
	v_lshlrev_b32_e32 v248, 16, v224
	v_and_b32_e32 v249, 0xffff0000, v224
	v_add_f32_e32 v236, v18, v248
	v_add_f32_e32 v237, v10, v249
	v_lshlrev_b32_e32 v248, 16, v225
	v_and_b32_e32 v249, 0xffff0000, v225
	v_add_f32_e32 v238, v6, v248
	v_add_f32_e32 v239, v2, v249
	s_add_u32 s60, s58, 0x164000
	s_addc_u32 s61, s59, 0
	global_store_dwordx4 v245, v[236:239], s[60:61]
	s_waitcnt vmcnt(31)
	v_lshlrev_b32_e32 v248, 16, v226
	v_and_b32_e32 v249, 0xffff0000, v226
	v_add_f32_e32 v240, v19, v248
	v_add_f32_e32 v241, v11, v249
	v_lshlrev_b32_e32 v248, 16, v227
	v_and_b32_e32 v249, 0xffff0000, v227
	v_add_f32_e32 v242, v7, v248
	v_add_f32_e32 v243, v3, v249
	s_add_u32 s62, s58, 0x166000
	s_addc_u32 s63, s59, 0
	global_store_dwordx4 v245, v[240:243], s[62:63]
	s_andn2_b64 vcc, exec, s[0:1]
	s_mov_b64 s[0:1], -1
	s_cbranch_vccnz .LBB0_1617
	s_andn2_b64 vcc, exec, s[6:7]
	s_cbranch_vccnz .LBB0_1616
	s_barrier
	s_branch .LBB0_1616
